# prompt attention: Q pre-scaled by softmax scale in f32 in the Q-proj epilogue (single bf16 rounding), running max rides in QK MFMA C operand, rescale as rare branch
# speedup vs baseline: 1.0371x; 1.0165x over previous
.LBB0_556:
	s_cmp_lt_u32 s6, 64
	s_cbranch_scc0 .Lq_noscale
	s_nop 7
	v_mul_f32_e32 v2, 0x3e16c740, v2
	v_mul_f32_e32 v3, 0x3e16c740, v3
	v_mul_f32_e32 v4, 0x3e16c740, v4
	v_mul_f32_e32 v5, 0x3e16c740, v5
	v_mul_f32_e32 v6, 0x3e16c740, v6
	v_mul_f32_e32 v7, 0x3e16c740, v7
	v_mul_f32_e32 v8, 0x3e16c740, v8
	v_mul_f32_e32 v9, 0x3e16c740, v9
	v_mul_f32_e32 v10, 0x3e16c740, v10
	v_mul_f32_e32 v11, 0x3e16c740, v11
	v_mul_f32_e32 v12, 0x3e16c740, v12
	v_mul_f32_e32 v13, 0x3e16c740, v13
	v_mul_f32_e32 v14, 0x3e16c740, v14
	v_mul_f32_e32 v15, 0x3e16c740, v15
	v_mul_f32_e32 v16, 0x3e16c740, v16
	v_mul_f32_e32 v17, 0x3e16c740, v17
	v_mul_f32_e32 v18, 0x3e16c740, v18
	v_mul_f32_e32 v19, 0x3e16c740, v19
	v_mul_f32_e32 v20, 0x3e16c740, v20
	v_mul_f32_e32 v21, 0x3e16c740, v21
	v_mul_f32_e32 v22, 0x3e16c740, v22
	v_mul_f32_e32 v23, 0x3e16c740, v23
	v_mul_f32_e32 v24, 0x3e16c740, v24
	v_mul_f32_e32 v25, 0x3e16c740, v25
	v_mul_f32_e32 v26, 0x3e16c740, v26
	v_mul_f32_e32 v27, 0x3e16c740, v27
	v_mul_f32_e32 v28, 0x3e16c740, v28
	v_mul_f32_e32 v29, 0x3e16c740, v29
	v_mul_f32_e32 v30, 0x3e16c740, v30
	v_mul_f32_e32 v31, 0x3e16c740, v31
	v_mul_f32_e32 v32, 0x3e16c740, v32
	v_mul_f32_e32 v33, 0x3e16c740, v33
	v_mul_f32_e32 v34, 0x3e16c740, v34
	v_mul_f32_e32 v35, 0x3e16c740, v35
	v_mul_f32_e32 v36, 0x3e16c740, v36
	v_mul_f32_e32 v37, 0x3e16c740, v37
	v_mul_f32_e32 v38, 0x3e16c740, v38
	v_mul_f32_e32 v39, 0x3e16c740, v39
	v_mul_f32_e32 v40, 0x3e16c740, v40
	v_mul_f32_e32 v41, 0x3e16c740, v41
	v_mul_f32_e32 v42, 0x3e16c740, v42
	v_mul_f32_e32 v43, 0x3e16c740, v43
	v_mul_f32_e32 v44, 0x3e16c740, v44
	v_mul_f32_e32 v45, 0x3e16c740, v45
	v_mul_f32_e32 v46, 0x3e16c740, v46
	v_mul_f32_e32 v47, 0x3e16c740, v47
	v_mul_f32_e32 v48, 0x3e16c740, v48
	v_mul_f32_e32 v49, 0x3e16c740, v49
	v_mul_f32_e32 v50, 0x3e16c740, v50
	v_mul_f32_e32 v51, 0x3e16c740, v51
	v_mul_f32_e32 v52, 0x3e16c740, v52
	v_mul_f32_e32 v53, 0x3e16c740, v53
	v_mul_f32_e32 v54, 0x3e16c740, v54
	v_mul_f32_e32 v55, 0x3e16c740, v55
	v_mul_f32_e32 v56, 0x3e16c740, v56
	v_mul_f32_e32 v57, 0x3e16c740, v57
	v_mul_f32_e32 v58, 0x3e16c740, v58
	v_mul_f32_e32 v59, 0x3e16c740, v59
	v_mul_f32_e32 v60, 0x3e16c740, v60
	v_mul_f32_e32 v61, 0x3e16c740, v61
	v_mul_f32_e32 v62, 0x3e16c740, v62
	v_mul_f32_e32 v63, 0x3e16c740, v63
	v_mul_f32_e32 v64, 0x3e16c740, v64
	v_mul_f32_e32 v65, 0x3e16c740, v65
	v_mul_f32_e32 v66, 0x3e16c740, v66
	v_mul_f32_e32 v67, 0x3e16c740, v67
	v_mul_f32_e32 v68, 0x3e16c740, v68
	v_mul_f32_e32 v69, 0x3e16c740, v69
	v_mul_f32_e32 v70, 0x3e16c740, v70
	v_mul_f32_e32 v71, 0x3e16c740, v71
	v_mul_f32_e32 v72, 0x3e16c740, v72
	v_mul_f32_e32 v73, 0x3e16c740, v73
	v_mul_f32_e32 v74, 0x3e16c740, v74
	v_mul_f32_e32 v75, 0x3e16c740, v75
	v_mul_f32_e32 v76, 0x3e16c740, v76
	v_mul_f32_e32 v77, 0x3e16c740, v77
	v_mul_f32_e32 v78, 0x3e16c740, v78
	v_mul_f32_e32 v79, 0x3e16c740, v79
	v_mul_f32_e32 v80, 0x3e16c740, v80
	v_mul_f32_e32 v81, 0x3e16c740, v81
	v_mul_f32_e32 v82, 0x3e16c740, v82
	v_mul_f32_e32 v83, 0x3e16c740, v83
	v_mul_f32_e32 v84, 0x3e16c740, v84
	v_mul_f32_e32 v85, 0x3e16c740, v85
	v_mul_f32_e32 v86, 0x3e16c740, v86
	v_mul_f32_e32 v87, 0x3e16c740, v87
	v_mul_f32_e32 v88, 0x3e16c740, v88
	v_mul_f32_e32 v89, 0x3e16c740, v89
	v_mul_f32_e32 v90, 0x3e16c740, v90
	v_mul_f32_e32 v91, 0x3e16c740, v91
	v_mul_f32_e32 v92, 0x3e16c740, v92
	v_mul_f32_e32 v93, 0x3e16c740, v93
	v_mul_f32_e32 v94, 0x3e16c740, v94
	v_mul_f32_e32 v95, 0x3e16c740, v95
	v_mul_f32_e32 v96, 0x3e16c740, v96
	v_mul_f32_e32 v97, 0x3e16c740, v97
	v_mul_f32_e32 v98, 0x3e16c740, v98
	v_mul_f32_e32 v99, 0x3e16c740, v99
	v_mul_f32_e32 v100, 0x3e16c740, v100
	v_mul_f32_e32 v101, 0x3e16c740, v101
	v_mul_f32_e32 v102, 0x3e16c740, v102
	v_mul_f32_e32 v103, 0x3e16c740, v103
	v_mul_f32_e32 v104, 0x3e16c740, v104
	v_mul_f32_e32 v105, 0x3e16c740, v105
	v_mul_f32_e32 v106, 0x3e16c740, v106
	v_mul_f32_e32 v107, 0x3e16c740, v107
	v_mul_f32_e32 v108, 0x3e16c740, v108
	v_mul_f32_e32 v109, 0x3e16c740, v109
	v_mul_f32_e32 v110, 0x3e16c740, v110
	v_mul_f32_e32 v111, 0x3e16c740, v111
	v_mul_f32_e32 v112, 0x3e16c740, v112
	v_mul_f32_e32 v113, 0x3e16c740, v113
	v_mul_f32_e32 v114, 0x3e16c740, v114
	v_mul_f32_e32 v115, 0x3e16c740, v115
	v_mul_f32_e32 v116, 0x3e16c740, v116
	v_mul_f32_e32 v117, 0x3e16c740, v117
	v_mul_f32_e32 v118, 0x3e16c740, v118
	v_mul_f32_e32 v119, 0x3e16c740, v119
	v_mul_f32_e32 v120, 0x3e16c740, v120
	v_mul_f32_e32 v121, 0x3e16c740, v121
	v_mul_f32_e32 v122, 0x3e16c740, v122
	v_mul_f32_e32 v123, 0x3e16c740, v123
	v_mul_f32_e32 v124, 0x3e16c740, v124
	v_mul_f32_e32 v125, 0x3e16c740, v125
	v_mul_f32_e32 v126, 0x3e16c740, v126
	v_mul_f32_e32 v127, 0x3e16c740, v127
	v_mul_f32_e32 v128, 0x3e16c740, v128
	v_mul_f32_e32 v129, 0x3e16c740, v129

.LBB0_819:
	v_max3_f32 v2, v4, v20, v5
	v_max3_f32 v49, v21, v6, v22
	s_ashr_i32 s21, s4, 1
	v_max3_f32 v2, v2, v7, v23
	v_max3_f32 v49, v49, v8, v24
	s_lshl_b32 s23, s35, 2
	v_max3_f32 v2, v2, v9, v25
	v_max3_f32 v49, v49, v10, v26
	v_and_b32_e32 v88, 16, v48
	v_max3_f32 v2, v2, v11, v27
	v_max3_f32 v49, v49, v12, v28
	s_mov_b32 s4, 1
	v_max3_f32 v2, v2, v13, v29
	v_max3_f32 v49, v49, v14, v30
	s_nop 0
	v_max3_f32 v2, v2, v15, v31
	v_max3_f32 v49, v49, v16, v32
	s_nop 0
	v_max3_f32 v2, v2, v17, v33
	v_max3_f32 v49, v49, v18, v34
	s_nop 0
	v_max3_f32 v2, v2, v49, v19
	s_nop 0
	v_max_f32_e32 v49, v35, v35
	v_max_f32_e32 v2, v2, v2
	v_max_f32_e32 v2, v2, v49
	v_mov_b32_e32 v49, v2
	s_nop 1
	v_permlane32_swap_b32_e32 v2, v49
	v_max_f32_e32 v49, v49, v49
	v_max_f32_e32 v2, v2, v2
	v_max_f32_e32 v2, v2, v49
	v_mul_f32_e32 v2, 0x3f800000, v2
	v_cmp_neq_f32_e32 vcc, s78, v2
	s_cmp_eq_u64 vcc, 0
	v_max_f32_e32 v49, 0xff800000, v2
	s_cselect_b64 vcc, -1, 0
	v_cndmask_b32_e32 v159, v49, v230, vcc
	v_fma_f32 v2, v4, 1.0, -v159
	v_exp_f32_e32 v84, v2
	v_fma_f32 v2, v20, 1.0, -v159
	v_exp_f32_e32 v85, v2
	v_fma_f32 v2, v5, 1.0, -v159
	v_fma_f32 v4, v21, 1.0, -v159
	v_exp_f32_e32 v2, v2
	v_exp_f32_e32 v20, v4
	v_add_f32_e32 v21, v85, v84
	v_cvt_pk_bf16_f32 v144, v84, v2
	v_pk_add_f32 v[4:5], v[20:21], v[2:3]
	v_cvt_pk_bf16_f32 v136, v85, v20
	v_pk_add_f32 v[50:51], v[4:5], v[4:5] op_sel_hi:[0,1]
	v_fma_f32 v4, v6, 1.0, -v159
	v_exp_f32_e32 v21, v4
	v_fma_f32 v4, v22, 1.0, -v159
	v_exp_f32_e32 v86, v4
	v_fma_f32 v4, v7, 1.0, -v159
	v_exp_f32_e32 v50, v4
	v_fma_f32 v4, v23, 1.0, -v159
	v_exp_f32_e32 v6, v4
	v_add_f32_e32 v7, v86, v21
	v_cvt_pk_bf16_f32 v145, v21, v50
	v_pk_add_f32 v[4:5], v[6:7], v[50:51]
	s_nop 0
	v_pk_add_f32 v[22:23], v[4:5], v[4:5] op_sel_hi:[0,1]
	v_fma_f32 v4, v8, 1.0, -v159
	v_exp_f32_e32 v7, v4
	v_fma_f32 v4, v24, 1.0, -v159
	v_exp_f32_e32 v51, v4
	v_fma_f32 v4, v9, 1.0, -v159
	v_exp_f32_e32 v22, v4
	v_fma_f32 v4, v25, 1.0, -v159
	v_exp_f32_e32 v8, v4
	v_add_f32_e32 v9, v51, v7
	v_cvt_pk_bf16_f32 v146, v7, v22
	v_cvt_pk_bf16_f32 v137, v86, v6
	v_pk_add_f32 v[4:5], v[8:9], v[22:23]
	v_cvt_pk_bf16_f32 v138, v51, v8
	v_pk_add_f32 v[24:25], v[4:5], v[4:5] op_sel_hi:[0,1]
	v_fma_f32 v4, v10, 1.0, -v159
	v_exp_f32_e32 v9, v4
	v_fma_f32 v4, v26, 1.0, -v159
	v_exp_f32_e32 v23, v4
	v_fma_f32 v4, v11, 1.0, -v159
	v_exp_f32_e32 v24, v4
	v_fma_f32 v4, v27, 1.0, -v159
	v_exp_f32_e32 v10, v4
	v_lshrrev_b32_e32 v4, 2, v48
	v_add_f32_e32 v11, v23, v9
	v_and_or_b32 v87, v4, 3, v154
	v_pk_add_f32 v[4:5], v[10:11], v[24:25]
	v_lshlrev_b32_e32 v48, 2, v48
	v_pk_add_f32 v[26:27], v[4:5], v[4:5] op_sel_hi:[0,1]
	v_fma_f32 v4, v12, 1.0, -v159
	v_exp_f32_e32 v11, v4
	v_fma_f32 v4, v28, 1.0, -v159
	v_exp_f32_e32 v25, v4
	v_fma_f32 v4, v13, 1.0, -v159
	v_exp_f32_e32 v26, v4
	v_fma_f32 v4, v29, 1.0, -v159
	v_exp_f32_e32 v12, v4
	v_add_f32_e32 v13, v25, v11
	v_mul_u32_u24_e32 v87, 0xc0, v87
	v_cvt_pk_bf16_f32 v147, v9, v24
	v_pk_add_f32 v[4:5], v[12:13], v[26:27]
	v_cvt_pk_bf16_f32 v140, v11, v26
	v_pk_add_f32 v[28:29], v[4:5], v[4:5] op_sel_hi:[0,1]
	v_fma_f32 v4, v14, 1.0, -v159
	v_exp_f32_e32 v13, v4
	v_fma_f32 v4, v30, 1.0, -v159
	v_exp_f32_e32 v27, v4
	v_fma_f32 v4, v15, 1.0, -v159
	v_exp_f32_e32 v28, v4
	v_fma_f32 v4, v31, 1.0, -v159
	v_exp_f32_e32 v14, v4
	v_add_f32_e32 v15, v27, v13
	v_cvt_pk_bf16_f32 v141, v13, v28
	v_cvt_pk_bf16_f32 v139, v23, v10
	v_pk_add_f32 v[4:5], v[14:15], v[28:29]
	v_cvt_pk_bf16_f32 v132, v25, v12
	v_pk_add_f32 v[30:31], v[4:5], v[4:5] op_sel_hi:[0,1]
	v_fma_f32 v4, v16, 1.0, -v159
	v_exp_f32_e32 v15, v4
	v_fma_f32 v4, v32, 1.0, -v159
	v_exp_f32_e32 v29, v4
	v_fma_f32 v4, v17, 1.0, -v159
	v_exp_f32_e32 v30, v4
	v_fma_f32 v4, v33, 1.0, -v159
	v_exp_f32_e32 v16, v4
	v_and_or_b32 v4, v48, 12, v88
	v_add_f32_e32 v17, v29, v15
	v_lshl_or_b32 v162, v4, 1, v87
	v_pk_add_f32 v[4:5], v[16:17], v[30:31]
	v_cvt_pk_bf16_f32 v142, v15, v30
	v_pk_add_f32 v[32:33], v[4:5], v[4:5] op_sel_hi:[0,1]
	v_fma_f32 v4, v18, 1.0, -v159
	v_exp_f32_e32 v17, v4
	v_fma_f32 v4, v34, 1.0, -v159
	v_exp_f32_e32 v31, v4
	v_fma_f32 v4, v19, 1.0, -v159
	v_exp_f32_e32 v32, v4
	v_fma_f32 v4, v35, 1.0, -v159
	v_exp_f32_e32 v18, v4
	v_sub_f32_e32 v4, 0xff800000, v49
	v_exp_f32_e32 v34, v4
	v_add_f32_e32 v19, v31, v17
	v_pk_add_f32 v[4:5], v[18:19], v[32:33]
	v_cvt_pk_bf16_f32 v143, v17, v32
	v_add_f32_e32 v5, v4, v5
	v_mul_f32_e32 v4, 0, v34
	v_cndmask_b32_e64 v4, v4, 0, vcc
	v_add_f32_e32 v152, v4, v5
	v_cvt_pk_bf16_f32 v133, v27, v14
	v_cvt_pk_bf16_f32 v134, v29, v16
	v_cvt_pk_bf16_f32 v135, v31, v18
	v_mad_u64_u32 v[20:21], s[50:51], v45, s80, v[44:45]
	v_mov_b32_e32 v5, v4
	v_mov_b32_e32 v6, v4
	v_mov_b32_e32 v7, v4
	v_mov_b32_e32 v8, v4
	v_mov_b32_e32 v9, v4
	v_mov_b32_e32 v10, v4
	v_mov_b32_e32 v11, v4
	v_mov_b32_e32 v12, v4
	v_mov_b32_e32 v13, v4
	v_mov_b32_e32 v14, v4
	v_mov_b32_e32 v15, v4
	v_mov_b32_e32 v16, v4
	v_mov_b32_e32 v17, v4
	v_mov_b32_e32 v18, v4
	v_mov_b32_e32 v19, v4
	v_add_u32_e32 v151, 0, v20
	s_andn2_b64 vcc, exec, s[2:3]
	s_waitcnt vmcnt(1)
	ds_write_b128 v157, v[40:43]
	ds_write_b64 v158, v[46:47] offset:128
	s_waitcnt vmcnt(0)
	ds_write_b128 v151, v[36:39] offset:26624
	s_waitcnt lgkmcnt(0)
	s_barrier
	s_cbranch_vccnz .LBB0_859
	v_mov_b64_e32 v[34:35], v[18:19]
	v_mov_b64_e32 v[98:99], v[66:67]
	v_mov_b64_e32 v[36:37], v[68:69]
	s_add_i32 s50, s23, -1
	s_mov_b32 s51, 1
	s_mov_b32 s52, s68
	s_mov_b32 s53, s67
	v_mov_b64_e32 v[32:33], v[16:17]
	v_mov_b64_e32 v[30:31], v[14:15]
	v_mov_b64_e32 v[28:29], v[12:13]
	v_mov_b64_e32 v[26:27], v[10:11]
	v_mov_b64_e32 v[24:25], v[8:9]
	v_mov_b64_e32 v[22:23], v[6:7]
	v_mov_b64_e32 v[20:21], v[4:5]
	v_mov_b64_e32 v[96:97], v[64:65]
	v_mov_b64_e32 v[94:95], v[62:63]
	v_mov_b64_e32 v[92:93], v[60:61]
	v_mov_b64_e32 v[90:91], v[58:59]
	v_mov_b64_e32 v[88:89], v[56:57]
	v_mov_b64_e32 v[86:87], v[54:55]
	v_mov_b64_e32 v[84:85], v[52:53]
	v_mov_b64_e32 v[38:39], v[70:71]
	v_mov_b64_e32 v[40:41], v[72:73]
	v_mov_b64_e32 v[42:43], v[74:75]
	v_mov_b64_e32 v[44:45], v[76:77]
	v_mov_b64_e32 v[46:47], v[78:79]
	v_mov_b64_e32 v[48:49], v[80:81]
	v_mov_b64_e32 v[50:51], v[82:83]
	v_xor_b32_e32 v234, 0x80000000, v159
	v_xor_b32_e32 v235, 0x80000000, v159
	v_xor_b32_e32 v236, 0x80000000, v159
	v_xor_b32_e32 v237, 0x80000000, v159
	v_xor_b32_e32 v238, 0x80000000, v159
	v_xor_b32_e32 v239, 0x80000000, v159
	v_xor_b32_e32 v240, 0x80000000, v159
	v_xor_b32_e32 v241, 0x80000000, v159
	v_xor_b32_e32 v242, 0x80000000, v159
	v_xor_b32_e32 v243, 0x80000000, v159
	v_xor_b32_e32 v244, 0x80000000, v159
	v_xor_b32_e32 v245, 0x80000000, v159
	v_xor_b32_e32 v246, 0x80000000, v159
	v_xor_b32_e32 v247, 0x80000000, v159
	v_xor_b32_e32 v248, 0x80000000, v159
	v_xor_b32_e32 v249, 0x80000000, v159
	v_sub_f32_e32 v84, v84, v159
	v_sub_f32_e32 v36, v36, v159
	v_sub_f32_e32 v85, v85, v159
	v_sub_f32_e32 v37, v37, v159
	v_sub_f32_e32 v86, v86, v159
	v_sub_f32_e32 v38, v38, v159
	v_sub_f32_e32 v87, v87, v159
	v_sub_f32_e32 v39, v39, v159
	v_sub_f32_e32 v88, v88, v159
	v_sub_f32_e32 v40, v40, v159
	v_sub_f32_e32 v89, v89, v159
	v_sub_f32_e32 v41, v41, v159
	v_sub_f32_e32 v90, v90, v159
	v_sub_f32_e32 v42, v42, v159
	v_sub_f32_e32 v91, v91, v159
	v_sub_f32_e32 v43, v43, v159
	v_sub_f32_e32 v92, v92, v159
	v_sub_f32_e32 v44, v44, v159
	v_sub_f32_e32 v93, v93, v159
	v_sub_f32_e32 v45, v45, v159
	v_sub_f32_e32 v94, v94, v159
	v_sub_f32_e32 v46, v46, v159
	v_sub_f32_e32 v95, v95, v159
	v_sub_f32_e32 v47, v47, v159
	v_sub_f32_e32 v96, v96, v159
	v_sub_f32_e32 v48, v48, v159
	v_sub_f32_e32 v97, v97, v159
	v_sub_f32_e32 v49, v49, v159
	v_sub_f32_e32 v98, v98, v159
	v_sub_f32_e32 v50, v50, v159
	v_sub_f32_e32 v99, v99, v159
	v_sub_f32_e32 v51, v51, v159
	v_add_u32_e32 v163, 0, v162
.LBB0_822:
	s_mov_b32 s5, 0
	s_add_i32 s2, s52, 0xfffff000
	buffer_load_dwordx2 v[108:109], v161, s[12:15], s2 offen
	s_add_i32 s3, s53, 0xfe020000
	buffer_load_dwordx4 v[104:107], v150, s[12:15], s3 offen
	s_add_i32 s4, s53, 0xfffe0000
	buffer_load_dwordx4 v[100:103], v150, s[12:15], s4 offen
	ds_read_b64_tr_b16 v[200:201], v162 offset:26624
	ds_read_b64_tr_b16 v[202:203], v162 offset:28160
	ds_read_b64_tr_b16 v[204:205], v162 offset:26688
	ds_read_b64_tr_b16 v[206:207], v162 offset:28224
	ds_read_b64_tr_b16 v[208:209], v162 offset:29696
	ds_read_b64_tr_b16 v[210:211], v162 offset:31232
	ds_read_b64_tr_b16 v[212:213], v162 offset:29760
	ds_read_b64_tr_b16 v[214:215], v162 offset:31296
	v_max3_f32 v2, v84, v36, v85
	v_max3_f32 v110, v37, v86, v38
	v_max3_f32 v2, v2, v87, v39
	v_max3_f32 v110, v110, v88, v40
	s_waitcnt lgkmcnt(6)
	v_mfma_f32_32x32x16_bf16 v[4:19], v[200:203], v[144:147], v[4:19]
	ds_read_b64_tr_b16 v[216:217], v162 offset:32768
	v_max3_f32 v2, v2, v89, v41
	v_max3_f32 v110, v110, v90, v42
	v_max3_f32 v2, v2, v91, v43
	v_max3_f32 v110, v110, v92, v44
	v_max3_f32 v2, v2, v93, v45
	s_waitcnt lgkmcnt(5)
	v_mfma_f32_32x32x16_bf16 v[20:35], v[204:207], v[144:147], v[20:35]
	ds_read_b64_tr_b16 v[218:219], v162 offset:34304
	ds_read_b64_tr_b16 v[250:251], v162 offset:32832
	v_max3_f32 v110, v110, v94, v46
	v_max3_f32 v2, v2, v95, v47
	v_max3_f32 v110, v110, v96, v48
	v_max3_f32 v2, v2, v97, v49
	v_max3_f32 v110, v110, v98, v50
	s_waitcnt lgkmcnt(5)
	v_mfma_f32_32x32x16_bf16 v[4:19], v[208:211], v[140:143], v[4:19]
	ds_read_b64_tr_b16 v[252:253], v162 offset:34368
	ds_read_b64_tr_b16 v[200:201], v162 offset:35840
	v_max3_f32 v2, v2, v110, v99
	v_max_f32_e32 v2, v2, v51
	v_mov_b32_e32 v111, v2
	s_nop 1
	v_permlane32_swap_b32_e32 v2, v111
	v_max_f32_e32 v2, v2, v111
	v_cmp_lt_f32_e32 vcc, 0x41000000, v2
	s_cbranch_vccz .Lpb_c0
	v_max_f32_e32 v222, 0, v2
	s_mov_b32 s5, 1
	v_exp_f32_e64 v220, -v222
	v_add_f32_e32 v159, v159, v222
	v_sub_f32_e32 v84, v84, v222
	v_sub_f32_e32 v36, v36, v222
	v_sub_f32_e32 v85, v85, v222
	v_sub_f32_e32 v37, v37, v222
	v_sub_f32_e32 v86, v86, v222
	v_sub_f32_e32 v38, v38, v222
	v_sub_f32_e32 v87, v87, v222
	v_sub_f32_e32 v39, v39, v222
	v_sub_f32_e32 v88, v88, v222
	v_sub_f32_e32 v40, v40, v222
	v_sub_f32_e32 v89, v89, v222
	v_sub_f32_e32 v41, v41, v222
	v_sub_f32_e32 v90, v90, v222
	v_sub_f32_e32 v42, v42, v222
	v_sub_f32_e32 v91, v91, v222
	v_sub_f32_e32 v43, v43, v222
	v_sub_f32_e32 v92, v92, v222
	v_sub_f32_e32 v44, v44, v222
	v_sub_f32_e32 v93, v93, v222
	v_sub_f32_e32 v45, v45, v222
	v_sub_f32_e32 v94, v94, v222
	v_sub_f32_e32 v46, v46, v222
	v_sub_f32_e32 v95, v95, v222
	v_sub_f32_e32 v47, v47, v222
	v_sub_f32_e32 v96, v96, v222
	v_sub_f32_e32 v48, v48, v222
	v_sub_f32_e32 v97, v97, v222
	v_sub_f32_e32 v49, v49, v222
	v_sub_f32_e32 v98, v98, v222
	v_sub_f32_e32 v50, v50, v222
	v_sub_f32_e32 v99, v99, v222
	v_sub_f32_e32 v51, v51, v222
	v_mul_f32_e32 v152, v152, v220
.Lpb_c0:
	s_waitcnt lgkmcnt(5)
	v_mfma_f32_32x32x16_bf16 v[20:35], v[212:215], v[140:143], v[20:35]
	ds_read_b64_tr_b16 v[202:203], v162 offset:37376
	ds_read_b64_tr_b16 v[204:205], v162 offset:35904
	v_exp_f32_e32 v84, v84
	v_exp_f32_e32 v36, v36
	v_exp_f32_e32 v85, v85
	v_exp_f32_e32 v37, v37
	v_add_f32_e32 v224, v84, v36
	s_waitcnt lgkmcnt(5)
	v_mfma_f32_32x32x16_bf16 v[4:19], v[216:219], v[136:139], v[4:19]
	ds_read_b64_tr_b16 v[206:207], v162 offset:37440
	ds_read_b128 v[164:167], v156 offset:51200
	v_exp_f32_e32 v86, v86
	v_cvt_pk_bf16_f32 v184, v84, v85
	v_exp_f32_e32 v38, v38
	v_add_f32_e32 v226, v85, v37
	v_cvt_pk_bf16_f32 v192, v36, v37
	s_waitcnt lgkmcnt(5)
	v_mfma_f32_32x32x16_bf16 v[20:35], v[250:253], v[136:139], v[20:35]
	ds_read_b128 v[176:179], v155 offset:0
	ds_read_b128 v[180:183], v155 offset:6656
	v_exp_f32_e32 v87, v87
	v_exp_f32_e32 v39, v39
	v_add_f32_e32 v124, v224, v226
	v_add_f32_e32 v233, v86, v38
	v_exp_f32_e32 v88, v88
	s_waitcnt lgkmcnt(5)
	v_mfma_f32_32x32x16_bf16 v[4:19], v[200:203], v[132:135], v[4:19]
	ds_read_b128 v[168:171], v156 offset:51232
	ds_read_b128 v[112:115], v155 offset:32
	v_cvt_pk_bf16_f32 v185, v86, v87
	v_exp_f32_e32 v40, v40
	v_add_f32_e32 v124, v124, v233
	v_add_f32_e32 v254, v87, v39
	v_cvt_pk_bf16_f32 v193, v38, v39
	s_waitcnt lgkmcnt(5)
	v_mfma_f32_32x32x16_bf16 v[20:35], v[204:207], v[132:135], v[20:35]
	ds_read_b128 v[116:119], v155 offset:6688
	ds_read_b128 v[172:175], v156 offset:51264
	v_exp_f32_e32 v89, v89
	v_exp_f32_e32 v41, v41
	v_add_f32_e32 v124, v124, v254
	v_add_f32_e32 v224, v88, v40
	v_exp_f32_e32 v90, v90
	s_waitcnt lgkmcnt(5)
	v_mfma_f32_32x32x16_bf16 v[52:67], v[176:179], v[164:167], v[234:249]
	ds_read_b128 v[120:123], v155 offset:64
	ds_read_b128 v[176:179], v155 offset:6720
	v_cvt_pk_bf16_f32 v186, v88, v89
	v_exp_f32_e32 v42, v42
	v_add_f32_e32 v124, v124, v224
	v_add_f32_e32 v226, v89, v41
	v_cvt_pk_bf16_f32 v194, v40, v41
	s_waitcnt lgkmcnt(6)
	v_mfma_f32_32x32x16_bf16 v[68:83], v[180:183], v[164:167], v[234:249]
	ds_read_b128 v[164:167], v156 offset:51296
	v_exp_f32_e32 v91, v91
	v_exp_f32_e32 v43, v43
	v_add_f32_e32 v124, v124, v226
	v_add_f32_e32 v233, v90, v42
	v_exp_f32_e32 v92, v92
	s_waitcnt lgkmcnt(5)
	v_mfma_f32_32x32x16_bf16 v[52:67], v[112:115], v[168:171], v[52:67]
	ds_read_b128 v[180:183], v155 offset:96
	ds_read_b128 v[112:115], v155 offset:6752
	v_cvt_pk_bf16_f32 v187, v90, v91
	v_exp_f32_e32 v44, v44
	v_add_f32_e32 v124, v124, v233
	v_add_f32_e32 v254, v91, v43
	v_cvt_pk_bf16_f32 v195, v42, v43
	s_waitcnt lgkmcnt(6)
	v_mfma_f32_32x32x16_bf16 v[68:83], v[116:119], v[168:171], v[68:83]
	ds_read_b128 v[168:171], v156 offset:51328
	v_exp_f32_e32 v93, v93
	v_exp_f32_e32 v45, v45
	v_add_f32_e32 v124, v124, v254
	v_add_f32_e32 v224, v92, v44
	v_exp_f32_e32 v94, v94
	s_waitcnt lgkmcnt(5)
	v_mfma_f32_32x32x16_bf16 v[52:67], v[120:123], v[172:175], v[52:67]
	ds_read_b128 v[116:119], v155 offset:128
	ds_read_b128 v[120:123], v155 offset:6784
	v_cvt_pk_bf16_f32 v188, v92, v93
	v_exp_f32_e32 v46, v46
	v_add_f32_e32 v124, v124, v224
	v_add_f32_e32 v226, v93, v45
	v_cvt_pk_bf16_f32 v196, v44, v45
	s_waitcnt lgkmcnt(6)
	v_mfma_f32_32x32x16_bf16 v[68:83], v[176:179], v[172:175], v[68:83]
	ds_read_b128 v[172:175], v156 offset:51360
	v_exp_f32_e32 v95, v95
	v_exp_f32_e32 v47, v47
	v_add_f32_e32 v124, v124, v226
	v_add_f32_e32 v233, v94, v46
	v_exp_f32_e32 v96, v96
	s_waitcnt lgkmcnt(5)
	v_mfma_f32_32x32x16_bf16 v[52:67], v[180:183], v[164:167], v[52:67]
	ds_read_b128 v[176:179], v155 offset:160
	ds_read_b128 v[180:183], v155 offset:6816
	v_cvt_pk_bf16_f32 v189, v94, v95
	v_exp_f32_e32 v48, v48
	v_add_f32_e32 v124, v124, v233
	v_add_f32_e32 v254, v95, v47
	v_cvt_pk_bf16_f32 v197, v46, v47
	s_waitcnt lgkmcnt(6)
	v_mfma_f32_32x32x16_bf16 v[68:83], v[112:115], v[164:167], v[68:83]
	v_exp_f32_e32 v97, v97
	v_exp_f32_e32 v49, v49
	v_add_f32_e32 v124, v124, v254
	v_add_f32_e32 v224, v96, v48
	v_exp_f32_e32 v98, v98
	s_waitcnt lgkmcnt(4)
	v_mfma_f32_32x32x16_bf16 v[52:67], v[116:119], v[168:171], v[52:67]
	v_cvt_pk_bf16_f32 v190, v96, v97
	v_exp_f32_e32 v50, v50
	v_add_f32_e32 v124, v124, v224
	v_add_f32_e32 v226, v97, v49
	v_cvt_pk_bf16_f32 v198, v48, v49
	s_waitcnt lgkmcnt(3)
	v_mfma_f32_32x32x16_bf16 v[68:83], v[120:123], v[168:171], v[68:83]
	v_exp_f32_e32 v99, v99
	v_exp_f32_e32 v51, v51
	v_add_f32_e32 v124, v124, v226
	v_add_f32_e32 v233, v98, v50
	v_cvt_pk_bf16_f32 v191, v98, v99
	s_waitcnt lgkmcnt(1)
	v_mfma_f32_32x32x16_bf16 v[52:67], v[176:179], v[172:175], v[52:67]
	v_add_f32_e32 v124, v124, v233
	v_add_f32_e32 v254, v99, v51
	v_cvt_pk_bf16_f32 v199, v50, v51
	v_add_f32_e32 v124, v124, v254
	v_add_f32_e32 v152, v152, v124
	s_waitcnt lgkmcnt(0)
	v_mfma_f32_32x32x16_bf16 v[68:83], v[180:183], v[172:175], v[68:83]
	s_cmp_eq_u32 s5, 0
	s_cbranch_scc1 .Lpb_nr0
	s_nop 11
	v_pk_mul_f32 v[4:5], v[220:221], v[4:5] op_sel_hi:[0,1]
	v_pk_mul_f32 v[6:7], v[220:221], v[6:7] op_sel_hi:[0,1]
	v_pk_mul_f32 v[8:9], v[220:221], v[8:9] op_sel_hi:[0,1]
	v_pk_mul_f32 v[10:11], v[220:221], v[10:11] op_sel_hi:[0,1]
	v_pk_mul_f32 v[12:13], v[220:221], v[12:13] op_sel_hi:[0,1]
	v_pk_mul_f32 v[14:15], v[220:221], v[14:15] op_sel_hi:[0,1]
	v_pk_mul_f32 v[16:17], v[220:221], v[16:17] op_sel_hi:[0,1]
	v_pk_mul_f32 v[18:19], v[220:221], v[18:19] op_sel_hi:[0,1]
	v_pk_mul_f32 v[20:21], v[220:221], v[20:21] op_sel_hi:[0,1]
	v_pk_mul_f32 v[22:23], v[220:221], v[22:23] op_sel_hi:[0,1]
	v_pk_mul_f32 v[24:25], v[220:221], v[24:25] op_sel_hi:[0,1]
	v_pk_mul_f32 v[26:27], v[220:221], v[26:27] op_sel_hi:[0,1]
	v_pk_mul_f32 v[28:29], v[220:221], v[28:29] op_sel_hi:[0,1]
	v_pk_mul_f32 v[30:31], v[220:221], v[30:31] op_sel_hi:[0,1]
	v_pk_mul_f32 v[32:33], v[220:221], v[32:33] op_sel_hi:[0,1]
	v_pk_mul_f32 v[34:35], v[220:221], v[34:35] op_sel_hi:[0,1]
	v_sub_f32_e32 v52, v52, v222
	v_sub_f32_e32 v68, v68, v222
	v_sub_f32_e32 v53, v53, v222
	v_sub_f32_e32 v69, v69, v222
	v_sub_f32_e32 v54, v54, v222
	v_sub_f32_e32 v70, v70, v222
	v_sub_f32_e32 v55, v55, v222
	v_sub_f32_e32 v71, v71, v222
	v_sub_f32_e32 v56, v56, v222
	v_sub_f32_e32 v72, v72, v222
	v_sub_f32_e32 v57, v57, v222
	v_sub_f32_e32 v73, v73, v222
	v_sub_f32_e32 v58, v58, v222
	v_sub_f32_e32 v74, v74, v222
	v_sub_f32_e32 v59, v59, v222
	v_sub_f32_e32 v75, v75, v222
	v_sub_f32_e32 v60, v60, v222
	v_sub_f32_e32 v76, v76, v222
	v_sub_f32_e32 v61, v61, v222
	v_sub_f32_e32 v77, v77, v222
	v_sub_f32_e32 v62, v62, v222
	v_sub_f32_e32 v78, v78, v222
	v_sub_f32_e32 v63, v63, v222
	v_sub_f32_e32 v79, v79, v222
	v_sub_f32_e32 v64, v64, v222
	v_sub_f32_e32 v80, v80, v222
	v_sub_f32_e32 v65, v65, v222
	v_sub_f32_e32 v81, v81, v222
	v_sub_f32_e32 v66, v66, v222
	v_sub_f32_e32 v82, v82, v222
	v_sub_f32_e32 v67, v67, v222
	v_sub_f32_e32 v83, v83, v222
	v_sub_f32_e32 v234, v234, v222
	v_sub_f32_e32 v235, v235, v222
	v_sub_f32_e32 v236, v236, v222
	v_sub_f32_e32 v237, v237, v222
	v_sub_f32_e32 v238, v238, v222
	v_sub_f32_e32 v239, v239, v222
	v_sub_f32_e32 v240, v240, v222
	v_sub_f32_e32 v241, v241, v222
	v_sub_f32_e32 v242, v242, v222
	v_sub_f32_e32 v243, v243, v222
	v_sub_f32_e32 v244, v244, v222
	v_sub_f32_e32 v245, v245, v222
	v_sub_f32_e32 v246, v246, v222
	v_sub_f32_e32 v247, v247, v222
	v_sub_f32_e32 v248, v248, v222
	v_sub_f32_e32 v249, v249, v222
.Lpb_nr0:
	s_waitcnt vmcnt(1)
	ds_write_b128 v157, v[104:107] offset:13312
	ds_write_b64 v158, v[108:109] offset:13440
	s_waitcnt vmcnt(0)
	ds_write_b128 v151, v[100:103] offset:38912
	s_waitcnt lgkmcnt(0)
	s_barrier
	s_mov_b32 s5, 0
	buffer_load_dwordx2 v[108:109], v161, s[12:15], s52 offen
	s_add_i32 s3, s53, 0xfe040000
	buffer_load_dwordx4 v[104:107], v150, s[12:15], s3 offen
	buffer_load_dwordx4 v[100:103], v150, s[12:15], s53 offen
	ds_read_b64_tr_b16 v[200:201], v162 offset:38912
	ds_read_b64_tr_b16 v[202:203], v162 offset:40448
	ds_read_b64_tr_b16 v[204:205], v162 offset:38976
	ds_read_b64_tr_b16 v[206:207], v162 offset:40512
	ds_read_b64_tr_b16 v[208:209], v162 offset:41984
	ds_read_b64_tr_b16 v[210:211], v162 offset:43520
	ds_read_b64_tr_b16 v[212:213], v162 offset:42048
	ds_read_b64_tr_b16 v[214:215], v162 offset:43584
	v_max3_f32 v2, v52, v68, v53
	v_max3_f32 v110, v69, v54, v70
	v_max3_f32 v2, v2, v55, v71
	v_max3_f32 v110, v110, v56, v72
	s_waitcnt lgkmcnt(6)
	v_mfma_f32_32x32x16_bf16 v[4:19], v[200:203], v[184:187], v[4:19]
	ds_read_b64_tr_b16 v[216:217], v162 offset:45056
	v_max3_f32 v2, v2, v57, v73
	v_max3_f32 v110, v110, v58, v74
	v_max3_f32 v2, v2, v59, v75
	v_max3_f32 v110, v110, v60, v76
	v_max3_f32 v2, v2, v61, v77
	s_waitcnt lgkmcnt(5)
	v_mfma_f32_32x32x16_bf16 v[20:35], v[204:207], v[184:187], v[20:35]
	ds_read_b64_tr_b16 v[218:219], v162 offset:46592
	ds_read_b64_tr_b16 v[250:251], v162 offset:45120
	v_max3_f32 v110, v110, v62, v78
	v_max3_f32 v2, v2, v63, v79
	v_max3_f32 v110, v110, v64, v80
	v_max3_f32 v2, v2, v65, v81
	v_max3_f32 v110, v110, v66, v82
	s_waitcnt lgkmcnt(5)
	v_mfma_f32_32x32x16_bf16 v[4:19], v[208:211], v[188:191], v[4:19]
	ds_read_b64_tr_b16 v[252:253], v162 offset:46656
	ds_read_b64_tr_b16 v[200:201], v162 offset:48128
	v_max3_f32 v2, v2, v110, v67
	v_max_f32_e32 v2, v2, v83
	v_mov_b32_e32 v111, v2
	s_nop 1
	v_permlane32_swap_b32_e32 v2, v111
	v_max_f32_e32 v2, v2, v111
	v_cmp_lt_f32_e32 vcc, 0x41000000, v2
	s_cbranch_vccz .Lpb_c1
	v_max_f32_e32 v222, 0, v2
	s_mov_b32 s5, 1
	v_exp_f32_e64 v220, -v222
	v_add_f32_e32 v159, v159, v222
	v_sub_f32_e32 v52, v52, v222
	v_sub_f32_e32 v68, v68, v222
	v_sub_f32_e32 v53, v53, v222
	v_sub_f32_e32 v69, v69, v222
	v_sub_f32_e32 v54, v54, v222
	v_sub_f32_e32 v70, v70, v222
	v_sub_f32_e32 v55, v55, v222
	v_sub_f32_e32 v71, v71, v222
	v_sub_f32_e32 v56, v56, v222
	v_sub_f32_e32 v72, v72, v222
	v_sub_f32_e32 v57, v57, v222
	v_sub_f32_e32 v73, v73, v222
	v_sub_f32_e32 v58, v58, v222
	v_sub_f32_e32 v74, v74, v222
	v_sub_f32_e32 v59, v59, v222
	v_sub_f32_e32 v75, v75, v222
	v_sub_f32_e32 v60, v60, v222
	v_sub_f32_e32 v76, v76, v222
	v_sub_f32_e32 v61, v61, v222
	v_sub_f32_e32 v77, v77, v222
	v_sub_f32_e32 v62, v62, v222
	v_sub_f32_e32 v78, v78, v222
	v_sub_f32_e32 v63, v63, v222
	v_sub_f32_e32 v79, v79, v222
	v_sub_f32_e32 v64, v64, v222
	v_sub_f32_e32 v80, v80, v222
	v_sub_f32_e32 v65, v65, v222
	v_sub_f32_e32 v81, v81, v222
	v_sub_f32_e32 v66, v66, v222
	v_sub_f32_e32 v82, v82, v222
	v_sub_f32_e32 v67, v67, v222
	v_sub_f32_e32 v83, v83, v222
	v_mul_f32_e32 v152, v152, v220
.Lpb_c1:
	s_waitcnt lgkmcnt(5)
	v_mfma_f32_32x32x16_bf16 v[20:35], v[212:215], v[188:191], v[20:35]
	ds_read_b64_tr_b16 v[202:203], v162 offset:49664
	ds_read_b64_tr_b16 v[204:205], v162 offset:48192
	v_exp_f32_e32 v52, v52
	v_exp_f32_e32 v68, v68
	v_exp_f32_e32 v53, v53
	v_exp_f32_e32 v69, v69
	v_add_f32_e32 v224, v52, v68
	s_waitcnt lgkmcnt(5)
	v_mfma_f32_32x32x16_bf16 v[4:19], v[216:219], v[192:195], v[4:19]
	ds_read_b64_tr_b16 v[206:207], v162 offset:49728
	ds_read_b128 v[164:167], v156 offset:51200
	v_exp_f32_e32 v54, v54
	v_cvt_pk_bf16_f32 v144, v52, v53
	v_exp_f32_e32 v70, v70
	v_add_f32_e32 v226, v53, v69
	v_cvt_pk_bf16_f32 v136, v68, v69
	s_waitcnt lgkmcnt(5)
	v_mfma_f32_32x32x16_bf16 v[20:35], v[250:253], v[192:195], v[20:35]
	ds_read_b128 v[176:179], v155 offset:13312
	ds_read_b128 v[180:183], v155 offset:19968
	v_exp_f32_e32 v55, v55
	v_exp_f32_e32 v71, v71
	v_add_f32_e32 v124, v224, v226
	v_add_f32_e32 v233, v54, v70
	v_exp_f32_e32 v56, v56
	s_waitcnt lgkmcnt(5)
	v_mfma_f32_32x32x16_bf16 v[4:19], v[200:203], v[196:199], v[4:19]
	ds_read_b128 v[168:171], v156 offset:51232
	ds_read_b128 v[112:115], v155 offset:13344
	v_cvt_pk_bf16_f32 v145, v54, v55
	v_exp_f32_e32 v72, v72
	v_add_f32_e32 v124, v124, v233
	v_add_f32_e32 v254, v55, v71
	v_cvt_pk_bf16_f32 v137, v70, v71
	s_waitcnt lgkmcnt(5)
	v_mfma_f32_32x32x16_bf16 v[20:35], v[204:207], v[196:199], v[20:35]
	ds_read_b128 v[116:119], v155 offset:20000
	ds_read_b128 v[172:175], v156 offset:51264
	v_exp_f32_e32 v57, v57
	v_exp_f32_e32 v73, v73
	v_add_f32_e32 v124, v124, v254
	v_add_f32_e32 v224, v56, v72
	v_exp_f32_e32 v58, v58
	s_waitcnt lgkmcnt(5)
	v_mfma_f32_32x32x16_bf16 v[84:99], v[176:179], v[164:167], v[234:249]
	ds_read_b128 v[120:123], v155 offset:13376
	ds_read_b128 v[176:179], v155 offset:20032
	v_cvt_pk_bf16_f32 v146, v56, v57
	v_exp_f32_e32 v74, v74
	v_add_f32_e32 v124, v124, v224
	v_add_f32_e32 v226, v57, v73
	v_cvt_pk_bf16_f32 v138, v72, v73
	s_waitcnt lgkmcnt(6)
	v_mfma_f32_32x32x16_bf16 v[36:51], v[180:183], v[164:167], v[234:249]
	ds_read_b128 v[164:167], v156 offset:51296
	v_exp_f32_e32 v59, v59
	v_exp_f32_e32 v75, v75
	v_add_f32_e32 v124, v124, v226
	v_add_f32_e32 v233, v58, v74
	v_exp_f32_e32 v60, v60
	s_waitcnt lgkmcnt(5)
	v_mfma_f32_32x32x16_bf16 v[84:99], v[112:115], v[168:171], v[84:99]
	ds_read_b128 v[180:183], v155 offset:13408
	ds_read_b128 v[112:115], v155 offset:20064
	v_cvt_pk_bf16_f32 v147, v58, v59
	v_exp_f32_e32 v76, v76
	v_add_f32_e32 v124, v124, v233
	v_add_f32_e32 v254, v59, v75
	v_cvt_pk_bf16_f32 v139, v74, v75
	s_waitcnt lgkmcnt(6)
	v_mfma_f32_32x32x16_bf16 v[36:51], v[116:119], v[168:171], v[36:51]
	ds_read_b128 v[168:171], v156 offset:51328
	v_exp_f32_e32 v61, v61
	v_exp_f32_e32 v77, v77
	v_add_f32_e32 v124, v124, v254
	v_add_f32_e32 v224, v60, v76
	v_exp_f32_e32 v62, v62
	s_waitcnt lgkmcnt(5)
	v_mfma_f32_32x32x16_bf16 v[84:99], v[120:123], v[172:175], v[84:99]
	ds_read_b128 v[116:119], v155 offset:13440
	ds_read_b128 v[120:123], v155 offset:20096
	v_cvt_pk_bf16_f32 v140, v60, v61
	v_exp_f32_e32 v78, v78
	v_add_f32_e32 v124, v124, v224
	v_add_f32_e32 v226, v61, v77
	v_cvt_pk_bf16_f32 v132, v76, v77
	s_waitcnt lgkmcnt(6)
	v_mfma_f32_32x32x16_bf16 v[36:51], v[176:179], v[172:175], v[36:51]
	ds_read_b128 v[172:175], v156 offset:51360
	v_exp_f32_e32 v63, v63
	v_exp_f32_e32 v79, v79
	v_add_f32_e32 v124, v124, v226
	v_add_f32_e32 v233, v62, v78
	v_exp_f32_e32 v64, v64
	s_waitcnt lgkmcnt(5)
	v_mfma_f32_32x32x16_bf16 v[84:99], v[180:183], v[164:167], v[84:99]
	ds_read_b128 v[176:179], v155 offset:13472
	ds_read_b128 v[180:183], v155 offset:20128
	v_cvt_pk_bf16_f32 v141, v62, v63
	v_exp_f32_e32 v80, v80
	v_add_f32_e32 v124, v124, v233
	v_add_f32_e32 v254, v63, v79
	v_cvt_pk_bf16_f32 v133, v78, v79
	s_waitcnt lgkmcnt(6)
	v_mfma_f32_32x32x16_bf16 v[36:51], v[112:115], v[164:167], v[36:51]
	v_exp_f32_e32 v65, v65
	v_exp_f32_e32 v81, v81
	v_add_f32_e32 v124, v124, v254
	v_add_f32_e32 v224, v64, v80
	v_exp_f32_e32 v66, v66
	s_waitcnt lgkmcnt(4)
	v_mfma_f32_32x32x16_bf16 v[84:99], v[116:119], v[168:171], v[84:99]
	v_cvt_pk_bf16_f32 v142, v64, v65
	v_exp_f32_e32 v82, v82
	v_add_f32_e32 v124, v124, v224
	v_add_f32_e32 v226, v65, v81
	v_cvt_pk_bf16_f32 v134, v80, v81
	s_waitcnt lgkmcnt(3)
	v_mfma_f32_32x32x16_bf16 v[36:51], v[120:123], v[168:171], v[36:51]
	v_exp_f32_e32 v67, v67
	v_exp_f32_e32 v83, v83
	v_add_f32_e32 v124, v124, v226
	v_add_f32_e32 v233, v66, v82
	v_cvt_pk_bf16_f32 v143, v66, v67
	s_waitcnt lgkmcnt(1)
	v_mfma_f32_32x32x16_bf16 v[84:99], v[176:179], v[172:175], v[84:99]
	v_add_f32_e32 v124, v124, v233
	v_add_f32_e32 v254, v67, v83
	v_cvt_pk_bf16_f32 v135, v82, v83
	v_add_f32_e32 v124, v124, v254
	v_add_f32_e32 v152, v152, v124
	s_waitcnt lgkmcnt(0)
	v_mfma_f32_32x32x16_bf16 v[36:51], v[180:183], v[172:175], v[36:51]
	s_cmp_eq_u32 s5, 0
	s_cbranch_scc1 .Lpb_nr1
	s_nop 11
	v_pk_mul_f32 v[4:5], v[220:221], v[4:5] op_sel_hi:[0,1]
	v_pk_mul_f32 v[6:7], v[220:221], v[6:7] op_sel_hi:[0,1]
	v_pk_mul_f32 v[8:9], v[220:221], v[8:9] op_sel_hi:[0,1]
	v_pk_mul_f32 v[10:11], v[220:221], v[10:11] op_sel_hi:[0,1]
	v_pk_mul_f32 v[12:13], v[220:221], v[12:13] op_sel_hi:[0,1]
	v_pk_mul_f32 v[14:15], v[220:221], v[14:15] op_sel_hi:[0,1]
	v_pk_mul_f32 v[16:17], v[220:221], v[16:17] op_sel_hi:[0,1]
	v_pk_mul_f32 v[18:19], v[220:221], v[18:19] op_sel_hi:[0,1]
	v_pk_mul_f32 v[20:21], v[220:221], v[20:21] op_sel_hi:[0,1]
	v_pk_mul_f32 v[22:23], v[220:221], v[22:23] op_sel_hi:[0,1]
	v_pk_mul_f32 v[24:25], v[220:221], v[24:25] op_sel_hi:[0,1]
	v_pk_mul_f32 v[26:27], v[220:221], v[26:27] op_sel_hi:[0,1]
	v_pk_mul_f32 v[28:29], v[220:221], v[28:29] op_sel_hi:[0,1]
	v_pk_mul_f32 v[30:31], v[220:221], v[30:31] op_sel_hi:[0,1]
	v_pk_mul_f32 v[32:33], v[220:221], v[32:33] op_sel_hi:[0,1]
	v_pk_mul_f32 v[34:35], v[220:221], v[34:35] op_sel_hi:[0,1]
	v_sub_f32_e32 v84, v84, v222
	v_sub_f32_e32 v36, v36, v222
	v_sub_f32_e32 v85, v85, v222
	v_sub_f32_e32 v37, v37, v222
	v_sub_f32_e32 v86, v86, v222
	v_sub_f32_e32 v38, v38, v222
	v_sub_f32_e32 v87, v87, v222
	v_sub_f32_e32 v39, v39, v222
	v_sub_f32_e32 v88, v88, v222
	v_sub_f32_e32 v40, v40, v222
	v_sub_f32_e32 v89, v89, v222
	v_sub_f32_e32 v41, v41, v222
	v_sub_f32_e32 v90, v90, v222
	v_sub_f32_e32 v42, v42, v222
	v_sub_f32_e32 v91, v91, v222
	v_sub_f32_e32 v43, v43, v222
	v_sub_f32_e32 v92, v92, v222
	v_sub_f32_e32 v44, v44, v222
	v_sub_f32_e32 v93, v93, v222
	v_sub_f32_e32 v45, v45, v222
	v_sub_f32_e32 v94, v94, v222
	v_sub_f32_e32 v46, v46, v222
	v_sub_f32_e32 v95, v95, v222
	v_sub_f32_e32 v47, v47, v222
	v_sub_f32_e32 v96, v96, v222
	v_sub_f32_e32 v48, v48, v222
	v_sub_f32_e32 v97, v97, v222
	v_sub_f32_e32 v49, v49, v222
	v_sub_f32_e32 v98, v98, v222
	v_sub_f32_e32 v50, v50, v222
	v_sub_f32_e32 v99, v99, v222
	v_sub_f32_e32 v51, v51, v222
	v_sub_f32_e32 v234, v234, v222
	v_sub_f32_e32 v235, v235, v222
	v_sub_f32_e32 v236, v236, v222
	v_sub_f32_e32 v237, v237, v222
	v_sub_f32_e32 v238, v238, v222
	v_sub_f32_e32 v239, v239, v222
	v_sub_f32_e32 v240, v240, v222
	v_sub_f32_e32 v241, v241, v222
	v_sub_f32_e32 v242, v242, v222
	v_sub_f32_e32 v243, v243, v222
	v_sub_f32_e32 v244, v244, v222
	v_sub_f32_e32 v245, v245, v222
	v_sub_f32_e32 v246, v246, v222
	v_sub_f32_e32 v247, v247, v222
	v_sub_f32_e32 v248, v248, v222
	v_sub_f32_e32 v249, v249, v222
.Lpb_nr1:
	s_waitcnt vmcnt(1)
	ds_write_b128 v157, v[104:107]
	ds_write_b64 v158, v[108:109] offset:128
	s_waitcnt vmcnt(0)
	ds_write_b128 v151, v[100:103] offset:26624
	s_add_i32 s51, s51, 2
	s_add_i32 s53, s53, 0x40000
	s_addk_i32 s52, 0x2000
	s_waitcnt lgkmcnt(0)
	s_barrier
	s_cmp_lt_i32 s51, s50
	s_cbranch_scc1 .LBB0_822
	v_add_f32_e32 v84, v84, v159
	v_add_f32_e32 v36, v36, v159
	v_add_f32_e32 v85, v85, v159
	v_add_f32_e32 v37, v37, v159
	v_add_f32_e32 v86, v86, v159
	v_add_f32_e32 v38, v38, v159
	v_add_f32_e32 v87, v87, v159
	v_add_f32_e32 v39, v39, v159
	v_add_f32_e32 v88, v88, v159
	v_add_f32_e32 v40, v40, v159
	v_add_f32_e32 v89, v89, v159
	v_add_f32_e32 v41, v41, v159
	v_add_f32_e32 v90, v90, v159
	v_add_f32_e32 v42, v42, v159
	v_add_f32_e32 v91, v91, v159
	v_add_f32_e32 v43, v43, v159
	v_add_f32_e32 v92, v92, v159
	v_add_f32_e32 v44, v44, v159
	v_add_f32_e32 v93, v93, v159
	v_add_f32_e32 v45, v45, v159
	v_add_f32_e32 v94, v94, v159
	v_add_f32_e32 v46, v46, v159
	v_add_f32_e32 v95, v95, v159
	v_add_f32_e32 v47, v47, v159
	v_add_f32_e32 v96, v96, v159
	v_add_f32_e32 v48, v48, v159
	v_add_f32_e32 v97, v97, v159
	v_add_f32_e32 v49, v49, v159
	v_add_f32_e32 v98, v98, v159
	v_add_f32_e32 v50, v50, v159
	v_add_f32_e32 v99, v99, v159
	v_add_f32_e32 v51, v51, v159
	s_branch .LBB0_860

.LBB0_860:
	ds_read_b128 v[52:55], v155
	ds_read_b128 v[62:65], v156 offset:51200
	ds_read_b128 v[66:69], v156 offset:51232
	ds_read_b128 v[56:59], v155 offset:32
	s_or_b32 s4, s23, 1
	s_lshl_b32 s2, s50, 17
	s_waitcnt lgkmcnt(2)
	v_mfma_f32_32x32x16_bf16 v[100:115], v[52:55], v[62:65], 0
	s_lshl_b32 s50, s4, 17
	s_lshl_b32 s3, s4, 12
	s_add_i32 s5, s50, s34
	s_or_b32 s3, s3, s63
	s_add_i32 s2, s2, s22
	s_waitcnt lgkmcnt(0)
	v_mfma_f32_32x32x16_bf16 v[100:115], v[56:59], v[66:69], v[100:115]
	ds_read_b128 v[52:55], v155 offset:64
	ds_read_b128 v[70:73], v156 offset:51264
	ds_read_b128 v[74:77], v156 offset:51296
	ds_read_b128 v[56:59], v155 offset:96
	s_waitcnt lgkmcnt(2)
	v_mfma_f32_32x32x16_bf16 v[100:115], v[52:55], v[70:73], v[100:115]
	ds_read_b128 v[52:55], v155 offset:128
	ds_read_b128 v[78:81], v156 offset:51328
	ds_read_b128 v[166:169], v156 offset:51360
	ds_read_b128 v[116:119], v155 offset:160
	buffer_load_dwordx2 v[60:61], v161, s[12:15], s3 offen
	s_waitcnt lgkmcnt(4)
	v_mfma_f32_32x32x16_bf16 v[100:115], v[56:59], v[74:77], v[100:115]
	s_waitcnt lgkmcnt(2)
	v_mfma_f32_32x32x16_bf16 v[100:115], v[52:55], v[78:81], v[100:115]
	buffer_load_dwordx4 v[56:59], v150, s[12:15], s5 offen
	buffer_load_dwordx4 v[52:55], v150, s[12:15], s2 offen
	ds_read_b128 v[120:123], v155 offset:6656
	ds_read_b128 v[170:173], v155 offset:6688
	ds_read_b128 v[174:177], v155 offset:6720
	ds_read_b128 v[178:181], v155 offset:6752
	ds_read_b128 v[182:185], v155 offset:6784
	ds_read_b128 v[186:189], v155 offset:6816
	v_max3_f32 v2, v84, v36, v85
	v_max3_f32 v82, v37, v86, v38
	s_nop 0
	v_max3_f32 v2, v2, v87, v39
	s_waitcnt lgkmcnt(6)
	v_mfma_f32_32x32x16_bf16 v[100:115], v[116:119], v[166:169], v[100:115]
	v_max3_f32 v82, v82, v88, v40
	v_max3_f32 v2, v2, v89, v41
	s_waitcnt lgkmcnt(5)
	v_mfma_f32_32x32x16_bf16 v[116:131], v[120:123], v[62:65], 0
	v_max3_f32 v62, v82, v90, v42
	v_max3_f32 v2, v2, v91, v43
	s_nop 0
	v_max3_f32 v62, v62, v92, v44
	v_max3_f32 v2, v2, v93, v45
	s_nop 0
	v_max3_f32 v62, v62, v94, v46
	s_waitcnt lgkmcnt(4)
	v_mfma_f32_32x32x16_bf16 v[116:131], v[170:173], v[66:69], v[116:131]
	v_max3_f32 v2, v2, v95, v47
	v_max3_f32 v62, v62, v96, v48
	s_nop 0
	v_max3_f32 v2, v2, v97, v49
	v_max3_f32 v62, v62, v98, v50
	s_nop 0
	v_max3_f32 v2, v2, v62, v99
	s_waitcnt lgkmcnt(3)
	v_mfma_f32_32x32x16_bf16 v[116:131], v[174:177], v[70:73], v[116:131]
	v_max_f32_e32 v2, v2, v2
	v_max_f32_e32 v62, v51, v51
	v_max_f32_e32 v2, v2, v62
	v_mov_b32_e32 v62, v2
	s_nop 1
	v_permlane32_swap_b32_e32 v2, v62
	v_max_f32_e32 v62, v62, v62
	s_waitcnt lgkmcnt(2)
	v_mfma_f32_32x32x16_bf16 v[116:131], v[178:181], v[74:77], v[116:131]
	v_max_f32_e32 v2, v2, v2
	v_max_f32_e32 v2, v2, v62
	v_mul_f32_e32 v2, 0x3f800000, v2
	v_add_f32_e32 v62, 0x41000000, v159
	v_cmp_gt_f32_e32 vcc, v2, v62
	v_max_f32_e32 v62, v159, v159
	v_max_f32_e32 v164, v62, v2
	s_waitcnt lgkmcnt(1)
	v_mfma_f32_32x32x16_bf16 v[116:131], v[182:185], v[78:81], v[116:131]
	v_sub_f32_e32 v2, v159, v164
	v_exp_f32_e32 v2, v2
	s_cmp_eq_u64 vcc, 0
	s_cselect_b64 s[2:3], -1, 0
	ds_read_b64_tr_b16 v[62:63], v163 offset:26624
	ds_read_b64_tr_b16 v[64:65], v163 offset:28160
	ds_read_b64_tr_b16 v[68:69], v163 offset:28224
	ds_read_b64_tr_b16 v[66:67], v163 offset:26688
	v_bfi_b32 v147, s62, v147, v147
	v_bfi_b32 v143, s62, v143, v143
	v_bfi_b32 v139, s62, v139, v139
	s_waitcnt lgkmcnt(2)
	v_mfma_f32_32x32x16_bf16 v[4:19], v[62:65], v[144:147], v[4:19]
	ds_read_b64_tr_b16 v[62:63], v163 offset:29696
	ds_read_b64_tr_b16 v[64:65], v163 offset:31232
	v_bfi_b32 v135, s62, v135, v135
	s_waitcnt lgkmcnt(2)
	v_mfma_f32_32x32x16_bf16 v[20:35], v[66:69], v[144:147], v[20:35]
	ds_read_b64_tr_b16 v[68:69], v163 offset:31296
	ds_read_b64_tr_b16 v[66:67], v163 offset:29760
	s_waitcnt lgkmcnt(2)
	v_mfma_f32_32x32x16_bf16 v[4:19], v[62:65], v[140:143], v[4:19]
	ds_read_b64_tr_b16 v[62:63], v163 offset:32768
	ds_read_b64_tr_b16 v[64:65], v163 offset:34304
	s_waitcnt lgkmcnt(2)
	v_mfma_f32_32x32x16_bf16 v[20:35], v[66:69], v[140:143], v[20:35]
	ds_read_b64_tr_b16 v[68:69], v163 offset:34368
	ds_read_b64_tr_b16 v[66:67], v163 offset:32832
	s_waitcnt lgkmcnt(2)
	v_mfma_f32_32x32x16_bf16 v[4:19], v[62:65], v[136:139], v[4:19]
	ds_read_b64_tr_b16 v[62:63], v163 offset:35840
	ds_read_b64_tr_b16 v[64:65], v163 offset:37376
	s_waitcnt lgkmcnt(2)
	v_mfma_f32_32x32x16_bf16 v[20:35], v[66:69], v[136:139], v[20:35]
	ds_read_b64_tr_b16 v[68:69], v163 offset:37440
	ds_read_b64_tr_b16 v[66:67], v163 offset:35904
	s_waitcnt lgkmcnt(2)
	v_mfma_f32_32x32x16_bf16 v[4:19], v[62:65], v[132:135], v[4:19]
	s_waitcnt lgkmcnt(0)
	v_mfma_f32_32x32x16_bf16 v[20:35], v[66:69], v[132:135], v[20:35]
	v_mfma_f32_32x32x16_bf16 v[116:131], v[186:189], v[166:169], v[116:131]
	s_cbranch_vccz .LBB0_862
	s_nop 7
	v_pk_mul_f32 v[18:19], v[2:3], v[18:19] op_sel_hi:[0,1]
	v_pk_mul_f32 v[16:17], v[2:3], v[16:17] op_sel_hi:[0,1]
	v_pk_mul_f32 v[14:15], v[2:3], v[14:15] op_sel_hi:[0,1]
	v_pk_mul_f32 v[12:13], v[2:3], v[12:13] op_sel_hi:[0,1]
	v_pk_mul_f32 v[10:11], v[2:3], v[10:11] op_sel_hi:[0,1]
	v_pk_mul_f32 v[8:9], v[2:3], v[8:9] op_sel_hi:[0,1]
	v_pk_mul_f32 v[6:7], v[2:3], v[6:7] op_sel_hi:[0,1]
	v_pk_mul_f32 v[4:5], v[2:3], v[4:5] op_sel_hi:[0,1]
	v_pk_mul_f32 v[34:35], v[2:3], v[34:35] op_sel_hi:[0,1]
	v_pk_mul_f32 v[32:33], v[2:3], v[32:33] op_sel_hi:[0,1]
	v_pk_mul_f32 v[30:31], v[2:3], v[30:31] op_sel_hi:[0,1]
	v_pk_mul_f32 v[28:29], v[2:3], v[28:29] op_sel_hi:[0,1]
	v_pk_mul_f32 v[26:27], v[2:3], v[26:27] op_sel_hi:[0,1]
	v_pk_mul_f32 v[24:25], v[2:3], v[24:25] op_sel_hi:[0,1]
	v_pk_mul_f32 v[22:23], v[2:3], v[22:23] op_sel_hi:[0,1]
	v_pk_mul_f32 v[20:21], v[2:3], v[20:21] op_sel_hi:[0,1]

.LBB0_864:
	v_cndmask_b32_e64 v159, v164, v159, s[2:3]
	v_xor_b32_e32 v142, 0x80000000, v159
	v_fmamk_f32 v84, v84, 0x3f800000, v142
	v_fmamk_f32 v36, v36, 0x3f800000, v142
	v_exp_f32_e32 v84, v84
	v_exp_f32_e32 v36, v36
	v_fmamk_f32 v85, v85, 0x3f800000, v142
	v_fmamk_f32 v37, v37, 0x3f800000, v142
	v_exp_f32_e32 v85, v85
	v_exp_f32_e32 v37, v37
	v_fmamk_f32 v86, v86, 0x3f800000, v142
	v_fmamk_f32 v38, v38, 0x3f800000, v142
	v_exp_f32_e32 v86, v86
	v_exp_f32_e32 v38, v38
	v_fmamk_f32 v87, v87, 0x3f800000, v142
	v_fmamk_f32 v39, v39, 0x3f800000, v142
	v_exp_f32_e32 v87, v87
	v_exp_f32_e32 v39, v39
	v_fmamk_f32 v88, v88, 0x3f800000, v142
	v_fmamk_f32 v40, v40, 0x3f800000, v142
	v_add_f32_e32 v147, v36, v84
	v_exp_f32_e32 v88, v88
	v_exp_f32_e32 v40, v40
	v_fmamk_f32 v89, v89, 0x3f800000, v142
	v_fmamk_f32 v41, v41, 0x3f800000, v142
	v_fma_f32 v90, v90, 1.0, -v159
	v_fma_f32 v42, v42, 1.0, -v159
	v_fma_f32 v43, v43, 1.0, -v159
	v_add_f32_e32 v147, 0, v147
	v_add_f32_e32 v164, v37, v85
	v_exp_f32_e32 v89, v89
	v_exp_f32_e32 v41, v41
	v_exp_f32_e32 v90, v90
	v_exp_f32_e32 v42, v42
	v_fma_f32 v91, v91, 1.0, -v159
	v_exp_f32_e32 v144, v43
	v_add_f32_e32 v147, v164, v147
	v_add_f32_e32 v164, v38, v86
	v_exp_f32_e32 v143, v91
	v_fma_f32 v43, v98, 1.0, -v159
	v_add_f32_e32 v147, v164, v147
	v_add_f32_e32 v164, v39, v87
	v_fmamk_f32 v92, v92, 0x3f800000, v142
	v_fmamk_f32 v44, v44, 0x3f800000, v142
	v_exp_f32_e32 v98, v43
	v_fma_f32 v43, v50, 1.0, -v159
	v_add_f32_e32 v147, v164, v147
	v_add_f32_e32 v164, v40, v88
	v_exp_f32_e32 v92, v92
	v_exp_f32_e32 v44, v44
	v_fmamk_f32 v93, v93, 0x3f800000, v142
	v_fmamk_f32 v45, v45, 0x3f800000, v142
	v_exp_f32_e32 v50, v43
	v_fma_f32 v43, v99, 1.0, -v159
	v_add_f32_e32 v147, v164, v147
	v_add_f32_e32 v164, v41, v89
	v_exp_f32_e32 v93, v93
	v_exp_f32_e32 v45, v45
	v_fmamk_f32 v94, v94, 0x3f800000, v142
	v_fmamk_f32 v46, v46, 0x3f800000, v142
	v_exp_f32_e32 v145, v43
	v_fma_f32 v43, v51, 1.0, -v159
	v_cvt_pk_bf16_f32 v51, v42, v144
	v_add_f32_e32 v147, v164, v147
	v_add_f32_e32 v42, v42, v90
	v_exp_f32_e32 v94, v94
	v_exp_f32_e32 v46, v46
	v_fmamk_f32 v95, v95, 0x3f800000, v142
	v_fmamk_f32 v47, v47, 0x3f800000, v142
	v_cvt_pk_bf16_f32 v99, v90, v143
	v_add_f32_e32 v42, v42, v147
	v_add_f32_e32 v90, v144, v143
	v_exp_f32_e32 v95, v95
	v_exp_f32_e32 v47, v47
	v_fmamk_f32 v96, v96, 0x3f800000, v142
	v_fmamk_f32 v48, v48, 0x3f800000, v142
	v_add_f32_e32 v42, v90, v42
	v_add_f32_e32 v90, v44, v92
	v_exp_f32_e32 v143, v96
	v_exp_f32_e32 v144, v48
	v_fmamk_f32 v48, v97, 0x3f800000, v142
	v_fmac_f32_e32 v142, 0x3f800000, v49
	v_add_f32_e32 v42, v90, v42
	v_add_f32_e32 v90, v45, v93
	v_exp_f32_e32 v48, v48
	v_exp_f32_e32 v142, v142
	v_add_f32_e32 v42, v90, v42
	v_add_f32_e32 v90, v46, v94
	v_exp_f32_e32 v146, v43
	v_add_f32_e32 v42, v90, v42
	v_add_f32_e32 v90, v47, v95
	v_add_f32_e32 v42, v90, v42
	v_add_f32_e32 v49, v144, v143
	v_add_f32_e32 v42, v49, v42
	v_add_f32_e32 v49, v142, v48
	v_add_f32_e32 v42, v49, v42
	v_add_f32_e32 v49, v50, v98
	v_add_f32_e32 v42, v49, v42
	v_add_f32_e32 v49, v146, v145
	v_mul_f32_e32 v2, v152, v2
	v_cvt_pk_bf16_f32 v91, v98, v145
	v_add_f32_e32 v145, v49, v42
	v_cndmask_b32_e64 v2, v2, v152, s[2:3]
	v_cvt_pk_bf16_f32 v43, v50, v146
	s_cmp_lt_i32 s21, 0
	v_cvt_pk_bf16_f32 v96, v84, v85
	v_cvt_pk_bf16_f32 v97, v86, v87
	v_cvt_pk_bf16_f32 v98, v88, v89
	v_cvt_pk_bf16_f32 v88, v92, v93
	v_cvt_pk_bf16_f32 v89, v94, v95
	v_cvt_pk_bf16_f32 v90, v143, v48
	v_cvt_pk_bf16_f32 v48, v36, v37
	v_cvt_pk_bf16_f32 v49, v38, v39
	v_cvt_pk_bf16_f32 v50, v40, v41
	v_cvt_pk_bf16_f32 v40, v44, v45
	v_cvt_pk_bf16_f32 v41, v46, v47
	v_cvt_pk_bf16_f32 v42, v144, v142
	v_add_f32_e32 v152, v2, v145
	s_cbranch_scc1 .LBB0_866
	v_or_b32_e32 v2, 32, v154
	v_cmp_le_i32_e32 vcc, v2, v153
	v_or_b32_e32 v36, 33, v154
	v_max_f32_e32 v45, v159, v159
	v_cndmask_b32_e32 v2, v230, v116, vcc
	v_cmp_le_i32_e32 vcc, v154, v153
	s_nop 1
	v_cndmask_b32_e32 v37, v230, v100, vcc
	v_cmp_lt_i32_e32 vcc, v154, v153
	s_nop 1
	v_cndmask_b32_e32 v38, v230, v101, vcc
	v_cmp_le_i32_e32 vcc, v36, v153
	v_or_b32_e32 v36, 2, v154
	s_nop 0
	v_cndmask_b32_e32 v39, v230, v117, vcc
	v_cmp_le_i32_e32 vcc, v36, v153
	v_or_b32_e32 v36, 34, v154
	s_nop 0
	v_cndmask_b32_e32 v46, v230, v102, vcc
	v_cmp_le_i32_e32 vcc, v36, v153
	v_or_b32_e32 v36, 3, v154
	s_nop 0
	v_cndmask_b32_e32 v47, v230, v118, vcc
	v_cmp_le_i32_e32 vcc, v36, v153
	v_or_b32_e32 v36, 35, v154
	s_nop 0
	v_cndmask_b32_e32 v84, v230, v103, vcc
	v_cmp_le_i32_e32 vcc, v36, v153
	v_or_b32_e32 v36, 8, v154
	s_nop 0
	v_cndmask_b32_e32 v85, v230, v119, vcc
	v_cmp_le_i32_e32 vcc, v36, v153
	v_or_b32_e32 v36, 40, v154
	s_nop 0
	v_cndmask_b32_e32 v86, v230, v104, vcc
	v_cmp_le_i32_e32 vcc, v36, v153
	v_or_b32_e32 v36, 9, v154
	s_nop 0
	v_cndmask_b32_e32 v87, v230, v120, vcc
	v_cmp_le_i32_e32 vcc, v36, v153
	v_or_b32_e32 v36, 41, v154
	s_nop 0
	v_cndmask_b32_e32 v92, v230, v105, vcc
	v_cmp_le_i32_e32 vcc, v36, v153
	v_or_b32_e32 v36, 10, v154
	s_nop 0
	v_cndmask_b32_e32 v93, v230, v121, vcc
	v_cmp_le_i32_e32 vcc, v36, v153
	v_or_b32_e32 v36, 42, v154
	s_nop 0
	v_cndmask_b32_e32 v94, v230, v106, vcc
	v_cmp_le_i32_e32 vcc, v36, v153
	v_or_b32_e32 v36, 11, v154
	s_nop 0
	v_cndmask_b32_e32 v95, v230, v122, vcc
	v_cmp_le_i32_e32 vcc, v36, v153
	v_or_b32_e32 v36, 43, v154
	s_nop 0
	v_cndmask_b32_e32 v100, v230, v107, vcc
	v_cmp_le_i32_e32 vcc, v36, v153
	v_or_b32_e32 v36, 16, v154
	s_nop 0
	v_cndmask_b32_e32 v101, v230, v123, vcc
	v_cmp_le_i32_e32 vcc, v36, v153
	v_or_b32_e32 v36, 48, v154
	s_nop 0
	v_cndmask_b32_e32 v102, v230, v108, vcc
	v_cmp_le_i32_e32 vcc, v36, v153
	v_or_b32_e32 v36, 17, v154
	s_nop 0
	v_cndmask_b32_e32 v103, v230, v124, vcc
	v_cmp_le_i32_e32 vcc, v36, v153
	v_or_b32_e32 v36, 49, v154
	s_nop 0
	v_cndmask_b32_e32 v104, v230, v109, vcc
	v_cmp_le_i32_e32 vcc, v36, v153
	v_or_b32_e32 v36, 18, v154
	s_nop 0
	v_cndmask_b32_e32 v105, v230, v125, vcc
	v_cmp_le_i32_e32 vcc, v36, v153
	v_or_b32_e32 v36, 50, v154
	s_nop 0
	v_cndmask_b32_e32 v106, v230, v110, vcc
	v_cmp_le_i32_e32 vcc, v36, v153
	v_or_b32_e32 v36, 19, v154
	s_nop 0
	v_cndmask_b32_e32 v107, v230, v126, vcc
	v_cmp_le_i32_e32 vcc, v36, v153
	v_or_b32_e32 v36, 51, v154
	s_nop 0
	v_cndmask_b32_e32 v108, v230, v111, vcc
	v_cmp_le_i32_e32 vcc, v36, v153
	v_or_b32_e32 v36, 24, v154
	s_nop 0
	v_cndmask_b32_e32 v109, v230, v127, vcc
	v_cmp_le_i32_e32 vcc, v36, v153
	v_or_b32_e32 v36, 56, v154
	s_nop 0
	v_cndmask_b32_e32 v110, v230, v112, vcc
	v_cmp_le_i32_e32 vcc, v36, v153
	v_or_b32_e32 v36, 25, v154
	s_nop 0
	v_cndmask_b32_e32 v111, v230, v128, vcc
	v_cmp_le_i32_e32 vcc, v36, v153
	v_or_b32_e32 v36, 57, v154
	s_nop 0
	v_cndmask_b32_e32 v112, v230, v113, vcc
	v_cmp_le_i32_e32 vcc, v36, v153
	v_or_b32_e32 v36, 26, v154
	s_nop 0
	v_cndmask_b32_e32 v113, v230, v129, vcc
	v_cmp_le_i32_e32 vcc, v36, v153
	v_or_b32_e32 v36, 58, v154
	s_nop 0
	v_cndmask_b32_e32 v114, v230, v114, vcc
	v_cmp_le_i32_e32 vcc, v36, v153
	v_or_b32_e32 v36, 27, v154
	s_nop 0
	v_cndmask_b32_e32 v122, v230, v130, vcc
	v_cmp_le_i32_e32 vcc, v36, v153
	v_or_b32_e32 v36, 59, v154
	s_nop 0
	v_cndmask_b32_e32 v115, v230, v115, vcc
	v_cmp_le_i32_e32 vcc, v36, v153
	v_max3_f32 v36, v37, v2, v38
	v_max3_f32 v44, v39, v46, v47
	s_nop 0
	v_max3_f32 v36, v36, v84, v85
	v_max3_f32 v44, v44, v86, v87
	s_nop 0
	v_cndmask_b32_e32 v123, v230, v131, vcc
	v_max3_f32 v36, v36, v92, v93
	v_max3_f32 v44, v44, v94, v95
	s_nop 0
	v_max3_f32 v36, v36, v100, v101
	v_max3_f32 v44, v44, v102, v103
	s_nop 0
	v_max3_f32 v36, v36, v104, v105
	v_max3_f32 v44, v44, v106, v107
	s_nop 0
	v_max3_f32 v36, v36, v108, v109
	v_max3_f32 v44, v44, v110, v111
	s_nop 0
	v_max3_f32 v36, v36, v112, v113
	v_max3_f32 v44, v44, v114, v122
	s_nop 0
	v_max3_f32 v36, v36, v44, v115
	v_max_f32_e32 v44, v123, v123
	v_max_f32_e32 v36, v36, v36
	v_max_f32_e32 v36, v36, v44
	v_mov_b32_e32 v44, v36
	s_nop 1
	v_permlane32_swap_b32_e32 v36, v44
	v_max_f32_e32 v44, v44, v44
	v_max_f32_e32 v36, v36, v36
	v_max_f32_e32 v36, v36, v44
	v_mul_f32_e32 v36, 0x3f800000, v36
	v_add_f32_e32 v44, 0x41000000, v159
	v_cmp_gt_f32_e32 vcc, v36, v44
	s_cmp_lg_u64 vcc, 0
	v_max_f32_e32 v45, v45, v36
	s_cselect_b64 s[2:3], -1, 0
	v_sub_f32_e32 v116, v159, v45
	v_cndmask_b32_e64 v159, v159, v45, s[2:3]
	v_fma_f32 v37, v37, 1.0, -v159
	v_fma_f32 v2, v2, 1.0, -v159
	v_exp_f32_e32 v37, v37
	v_exp_f32_e32 v125, v2
	v_fma_f32 v2, v38, 1.0, -v159
	v_fma_f32 v38, v39, 1.0, -v159
	v_exp_f32_e32 v2, v2
	v_exp_f32_e32 v38, v38
	v_add_f32_e32 v39, v125, v37
	v_exp_f32_e32 v124, v116
	v_pk_add_f32 v[44:45], v[38:39], v[2:3]
	s_nop 0
	v_pk_add_f32 v[44:45], v[44:45], v[44:45] op_sel_hi:[0,1]
	v_fma_f32 v39, v46, 1.0, -v159
	v_fma_f32 v44, v47, 1.0, -v159
	v_exp_f32_e32 v39, v39
	v_exp_f32_e32 v126, v44
	v_fma_f32 v44, v84, 1.0, -v159
	v_fma_f32 v46, v85, 1.0, -v159
	v_exp_f32_e32 v44, v44
	v_exp_f32_e32 v46, v46
	v_add_f32_e32 v47, v126, v39
	v_cndmask_b32_e64 v36, 1.0, v124, s[2:3]
	v_pk_add_f32 v[84:85], v[46:47], v[44:45]
	s_nop 0
	v_pk_add_f32 v[84:85], v[84:85], v[84:85] op_sel_hi:[0,1]
	v_fma_f32 v45, v86, 1.0, -v159
	v_fma_f32 v47, v87, 1.0, -v159
	v_exp_f32_e32 v45, v45
	v_exp_f32_e32 v47, v47
	v_fma_f32 v84, v92, 1.0, -v159
	v_fma_f32 v86, v93, 1.0, -v159
	v_exp_f32_e32 v84, v84
	v_exp_f32_e32 v86, v86
	v_add_f32_e32 v87, v47, v45
	v_pk_add_f32 v[92:93], v[86:87], v[84:85]
	s_nop 0
	v_pk_add_f32 v[92:93], v[92:93], v[92:93] op_sel_hi:[0,1]
	v_fma_f32 v85, v94, 1.0, -v159
	v_fma_f32 v87, v95, 1.0, -v159
	v_exp_f32_e32 v85, v85
	v_exp_f32_e32 v87, v87
	v_fma_f32 v92, v100, 1.0, -v159
	v_fma_f32 v94, v101, 1.0, -v159
	v_exp_f32_e32 v92, v92
	v_exp_f32_e32 v94, v94
	v_add_f32_e32 v95, v87, v85
	v_pk_add_f32 v[100:101], v[94:95], v[92:93]
	s_nop 0
	v_pk_add_f32 v[100:101], v[100:101], v[100:101] op_sel_hi:[0,1]
	v_fma_f32 v93, v102, 1.0, -v159
	v_fma_f32 v95, v103, 1.0, -v159
	v_exp_f32_e32 v93, v93
	v_exp_f32_e32 v95, v95
	v_fma_f32 v100, v104, 1.0, -v159
	v_fma_f32 v102, v105, 1.0, -v159
	v_exp_f32_e32 v100, v100
	v_exp_f32_e32 v102, v102
	v_add_f32_e32 v103, v95, v93
	v_pk_add_f32 v[104:105], v[102:103], v[100:101]
	s_nop 0
	v_pk_add_f32 v[104:105], v[104:105], v[104:105] op_sel_hi:[0,1]
	v_fma_f32 v101, v106, 1.0, -v159
	v_fma_f32 v103, v107, 1.0, -v159
	v_exp_f32_e32 v101, v101
	v_exp_f32_e32 v103, v103
	v_fma_f32 v104, v108, 1.0, -v159
	v_fma_f32 v106, v109, 1.0, -v159
	v_exp_f32_e32 v104, v104
	v_exp_f32_e32 v116, v106
	v_add_f32_e32 v117, v103, v101
	v_fma_f32 v108, v113, 1.0, -v159
	v_exp_f32_e32 v118, v108
	v_pk_add_f32 v[106:107], v[116:117], v[104:105]
	v_fma_f32 v105, v110, 1.0, -v159
	v_pk_add_f32 v[106:107], v[106:107], v[106:107] op_sel_hi:[0,1]
	v_fma_f32 v106, v111, 1.0, -v159
	v_exp_f32_e32 v105, v105
	v_exp_f32_e32 v117, v106
	v_fma_f32 v106, v112, 1.0, -v159
	v_exp_f32_e32 v106, v106
	v_cvt_pk_bf16_f32 v112, v37, v2
	v_add_f32_e32 v119, v117, v105
	v_cvt_pk_bf16_f32 v113, v39, v44
	v_pk_add_f32 v[108:109], v[118:119], v[106:107]
	v_fma_f32 v107, v114, 1.0, -v159
	v_pk_add_f32 v[120:121], v[108:109], v[108:109] op_sel_hi:[0,1]
	v_fma_f32 v108, v122, 1.0, -v159
	v_exp_f32_e32 v119, v108
	v_fma_f32 v108, v115, 1.0, -v159
	v_exp_f32_e32 v107, v107
	v_exp_f32_e32 v120, v108
	v_fma_f32 v108, v123, 1.0, -v159
	v_exp_f32_e32 v122, v108
	v_add_f32_e32 v123, v119, v107
	v_cvt_pk_bf16_f32 v114, v45, v84
	v_cvt_pk_bf16_f32 v115, v85, v92
	v_pk_add_f32 v[108:109], v[122:123], v[120:121]
	v_cvt_pk_bf16_f32 v110, v105, v106
	v_add_f32_e32 v108, v108, v109
	v_mul_f32_e32 v109, v152, v124
	v_cndmask_b32_e64 v109, v152, v109, s[2:3]
	v_add_f32_e32 v152, v109, v108
	v_cvt_pk_bf16_f32 v108, v93, v100
	v_cvt_pk_bf16_f32 v109, v101, v104
	v_cvt_pk_bf16_f32 v111, v107, v120
	v_cvt_pk_bf16_f32 v104, v125, v38
	v_cvt_pk_bf16_f32 v105, v126, v46
	v_cvt_pk_bf16_f32 v106, v47, v86
	v_cvt_pk_bf16_f32 v107, v87, v94
	v_cvt_pk_bf16_f32 v100, v95, v102
	v_cvt_pk_bf16_f32 v101, v103, v116
	v_cvt_pk_bf16_f32 v102, v117, v118
	v_cvt_pk_bf16_f32 v103, v119, v122
	s_branch .LBB0_867

.LBB0_874:
	s_cmp_gt_i32 s34, s21
	s_cbranch_scc1 .LBB0_876
	v_lshl_or_b32 v2, s34, 6, v154
	v_or_b32_e32 v100, 32, v2
	v_cmp_le_i32_e32 vcc, v100, v153
	s_nop 1
	v_cndmask_b32_e32 v68, v230, v68, vcc
	v_cmp_le_i32_e32 vcc, v2, v153
	s_nop 1
	v_cndmask_b32_e32 v100, v230, v52, vcc
	v_cmp_lt_i32_e32 vcc, v2, v153
	v_or_b32_e32 v52, 33, v2
	s_nop 0
	v_cndmask_b32_e32 v53, v230, v53, vcc
	v_cmp_le_i32_e32 vcc, v52, v153
	v_or_b32_e32 v52, 2, v2
	s_nop 0
	v_cndmask_b32_e32 v69, v230, v69, vcc
	v_cmp_le_i32_e32 vcc, v52, v153
	v_or_b32_e32 v52, 34, v2
	s_nop 0
	v_cndmask_b32_e32 v101, v230, v54, vcc
	v_cmp_le_i32_e32 vcc, v52, v153
	v_or_b32_e32 v52, 3, v2
	v_max_f32_e32 v54, v159, v159
	v_cndmask_b32_e32 v70, v230, v70, vcc
	v_cmp_le_i32_e32 vcc, v52, v153
	v_or_b32_e32 v52, 35, v2
	s_nop 0
	v_cndmask_b32_e32 v102, v230, v55, vcc
	v_cmp_le_i32_e32 vcc, v52, v153
	v_or_b32_e32 v52, 8, v2
	s_nop 0
	v_cndmask_b32_e32 v71, v230, v71, vcc
	v_cmp_le_i32_e32 vcc, v52, v153
	v_or_b32_e32 v52, 40, v2
	s_nop 0
	v_cndmask_b32_e32 v103, v230, v56, vcc
	v_cmp_le_i32_e32 vcc, v52, v153
	v_or_b32_e32 v52, 9, v2
	s_nop 0
	v_cndmask_b32_e32 v72, v230, v72, vcc
	v_cmp_le_i32_e32 vcc, v52, v153
	v_or_b32_e32 v52, 41, v2
	s_nop 0
	v_cndmask_b32_e32 v104, v230, v57, vcc
	v_cmp_le_i32_e32 vcc, v52, v153
	v_or_b32_e32 v52, 10, v2
	s_nop 0
	v_cndmask_b32_e32 v73, v230, v73, vcc
	v_cmp_le_i32_e32 vcc, v52, v153
	v_or_b32_e32 v52, 42, v2
	s_nop 0
	v_cndmask_b32_e32 v105, v230, v58, vcc
	v_cmp_le_i32_e32 vcc, v52, v153
	v_or_b32_e32 v52, 11, v2
	s_nop 0
	v_cndmask_b32_e32 v74, v230, v74, vcc
	v_cmp_le_i32_e32 vcc, v52, v153
	v_or_b32_e32 v52, 43, v2
	s_nop 0
	v_cndmask_b32_e32 v106, v230, v59, vcc
	v_cmp_le_i32_e32 vcc, v52, v153
	v_or_b32_e32 v52, 16, v2
	s_nop 0
	v_cndmask_b32_e32 v75, v230, v75, vcc
	v_cmp_le_i32_e32 vcc, v52, v153
	v_or_b32_e32 v52, 48, v2
	s_nop 0
	v_cndmask_b32_e32 v107, v230, v60, vcc
	v_cmp_le_i32_e32 vcc, v52, v153
	v_or_b32_e32 v52, 17, v2
	s_nop 0
	v_cndmask_b32_e32 v76, v230, v76, vcc
	v_cmp_le_i32_e32 vcc, v52, v153
	v_or_b32_e32 v52, 49, v2
	s_nop 0
	v_cndmask_b32_e32 v108, v230, v61, vcc
	v_cmp_le_i32_e32 vcc, v52, v153
	v_or_b32_e32 v52, 18, v2
	s_nop 0
	v_cndmask_b32_e32 v77, v230, v77, vcc
	v_cmp_le_i32_e32 vcc, v52, v153
	v_or_b32_e32 v52, 50, v2
	s_nop 0
	v_cndmask_b32_e32 v109, v230, v62, vcc
	v_cmp_le_i32_e32 vcc, v52, v153
	v_or_b32_e32 v52, 19, v2
	s_nop 0
	v_cndmask_b32_e32 v78, v230, v78, vcc
	v_cmp_le_i32_e32 vcc, v52, v153
	v_or_b32_e32 v52, 51, v2
	s_nop 0
	v_cndmask_b32_e32 v110, v230, v63, vcc
	v_cmp_le_i32_e32 vcc, v52, v153
	v_or_b32_e32 v52, 24, v2
	s_nop 0
	v_cndmask_b32_e32 v79, v230, v79, vcc
	v_cmp_le_i32_e32 vcc, v52, v153
	v_or_b32_e32 v52, 56, v2
	s_nop 0
	v_cndmask_b32_e32 v111, v230, v64, vcc
	v_cmp_le_i32_e32 vcc, v52, v153
	v_or_b32_e32 v52, 25, v2
	s_nop 0
	v_cndmask_b32_e32 v80, v230, v80, vcc
	v_cmp_le_i32_e32 vcc, v52, v153
	v_or_b32_e32 v52, 57, v2
	s_nop 0
	v_cndmask_b32_e32 v112, v230, v65, vcc
	v_cmp_le_i32_e32 vcc, v52, v153
	v_or_b32_e32 v52, 26, v2
	s_nop 0
	v_cndmask_b32_e32 v81, v230, v81, vcc
	v_cmp_le_i32_e32 vcc, v52, v153
	v_or_b32_e32 v52, 58, v2
	s_nop 0
	v_cndmask_b32_e32 v113, v230, v66, vcc
	v_cmp_le_i32_e32 vcc, v52, v153
	v_or_b32_e32 v52, 27, v2
	v_or_b32_e32 v2, 59, v2
	v_cndmask_b32_e32 v82, v230, v82, vcc
	v_cmp_le_i32_e32 vcc, v52, v153
	s_nop 1
	v_cndmask_b32_e32 v114, v230, v67, vcc
	v_cmp_le_i32_e32 vcc, v2, v153
	v_max3_f32 v2, v100, v68, v53
	v_max3_f32 v52, v69, v101, v70
	s_nop 0
	v_max3_f32 v2, v2, v102, v71
	v_max3_f32 v52, v52, v103, v72
	s_nop 0
	v_cndmask_b32_e32 v83, v230, v83, vcc
	v_max3_f32 v2, v2, v104, v73
	v_max3_f32 v52, v52, v105, v74
	s_nop 0
	v_max3_f32 v2, v2, v106, v75
	v_max3_f32 v52, v52, v107, v76
	s_nop 0
	v_max3_f32 v2, v2, v108, v77
	v_max3_f32 v52, v52, v109, v78
	s_nop 0
	v_max3_f32 v2, v2, v110, v79
	v_max3_f32 v52, v52, v111, v80
	s_nop 0
	v_max3_f32 v2, v2, v112, v81
	v_max3_f32 v52, v52, v113, v82
	s_nop 0
	v_max3_f32 v2, v2, v52, v114
	v_max_f32_e32 v52, v83, v83
	v_max_f32_e32 v2, v2, v2
	v_max_f32_e32 v2, v2, v52
	v_mov_b32_e32 v52, v2
	s_nop 1
	v_permlane32_swap_b32_e32 v2, v52
	v_max_f32_e32 v52, v52, v52
	v_max_f32_e32 v2, v2, v2
	v_max_f32_e32 v2, v2, v52
	v_mul_f32_e32 v2, 0x3f800000, v2
	v_add_f32_e32 v52, 0x41000000, v159
	v_cmp_gt_f32_e32 vcc, v2, v52
	s_cmp_lg_u64 vcc, 0
	v_max_f32_e32 v54, v54, v2
	s_cselect_b64 s[2:3], -1, 0
	v_sub_f32_e32 v55, v159, v54
	v_cndmask_b32_e64 v159, v159, v54, s[2:3]
	v_fma_f32 v2, v100, 1.0, -v159
	v_exp_f32_e32 v127, v2
	v_fma_f32 v2, v68, 1.0, -v159
	v_exp_f32_e32 v128, v2
	v_fma_f32 v2, v53, 1.0, -v159
	v_fma_f32 v53, v69, 1.0, -v159
	v_exp_f32_e32 v2, v2
	v_exp_f32_e32 v54, v53
	v_exp_f32_e32 v115, v55
	v_add_f32_e32 v55, v128, v127
	v_fma_f32 v53, v101, 1.0, -v159
	v_pk_add_f32 v[56:57], v[54:55], v[2:3]
	v_fma_f32 v55, v70, 1.0, -v159
	v_pk_add_f32 v[56:57], v[56:57], v[56:57] op_sel_hi:[0,1]
	v_exp_f32_e32 v53, v53
	v_exp_f32_e32 v55, v55
	v_fma_f32 v56, v102, 1.0, -v159
	v_fma_f32 v58, v71, 1.0, -v159
	v_exp_f32_e32 v56, v56
	v_exp_f32_e32 v58, v58
	v_add_f32_e32 v59, v55, v53
	v_fma_f32 v62, v73, 1.0, -v159
	v_exp_f32_e32 v62, v62
	v_pk_add_f32 v[60:61], v[58:59], v[56:57]
	v_fma_f32 v57, v103, 1.0, -v159
	v_pk_add_f32 v[60:61], v[60:61], v[60:61] op_sel_hi:[0,1]
	v_fma_f32 v59, v72, 1.0, -v159
	v_exp_f32_e32 v57, v57
	v_exp_f32_e32 v59, v59
	v_fma_f32 v60, v104, 1.0, -v159
	v_exp_f32_e32 v60, v60
	v_fma_f32 v66, v75, 1.0, -v159
	v_add_f32_e32 v63, v59, v57
	v_exp_f32_e32 v66, v66
	v_pk_add_f32 v[64:65], v[62:63], v[60:61]
	v_fma_f32 v61, v105, 1.0, -v159
	v_pk_add_f32 v[64:65], v[64:65], v[64:65] op_sel_hi:[0,1]
	v_fma_f32 v63, v74, 1.0, -v159
	v_exp_f32_e32 v61, v61
	v_exp_f32_e32 v63, v63
	v_fma_f32 v64, v106, 1.0, -v159
	v_exp_f32_e32 v64, v64
	v_fma_f32 v70, v77, 1.0, -v159
	v_add_f32_e32 v67, v63, v61
	v_exp_f32_e32 v70, v70
	v_pk_add_f32 v[68:69], v[66:67], v[64:65]
	v_fma_f32 v65, v107, 1.0, -v159
	v_pk_add_f32 v[68:69], v[68:69], v[68:69] op_sel_hi:[0,1]
	v_fma_f32 v67, v76, 1.0, -v159
	v_exp_f32_e32 v65, v65
	v_exp_f32_e32 v67, v67
	v_fma_f32 v68, v108, 1.0, -v159
	v_exp_f32_e32 v68, v68
	v_fma_f32 v74, v79, 1.0, -v159
	v_add_f32_e32 v71, v67, v65
	v_exp_f32_e32 v74, v74
	v_pk_add_f32 v[72:73], v[70:71], v[68:69]
	v_fma_f32 v69, v109, 1.0, -v159
	v_pk_add_f32 v[72:73], v[72:73], v[72:73] op_sel_hi:[0,1]
	v_fma_f32 v71, v78, 1.0, -v159
	v_exp_f32_e32 v69, v69
	v_exp_f32_e32 v71, v71
	v_fma_f32 v72, v110, 1.0, -v159
	v_exp_f32_e32 v72, v72
	v_fma_f32 v78, v81, 1.0, -v159
	v_add_f32_e32 v75, v71, v69
	v_exp_f32_e32 v78, v78
	v_pk_add_f32 v[76:77], v[74:75], v[72:73]
	v_fma_f32 v73, v111, 1.0, -v159
	v_pk_add_f32 v[76:77], v[76:77], v[76:77] op_sel_hi:[0,1]
	v_fma_f32 v75, v80, 1.0, -v159
	v_exp_f32_e32 v73, v73
	v_exp_f32_e32 v75, v75
	v_fma_f32 v76, v112, 1.0, -v159
	v_exp_f32_e32 v76, v76
	v_cndmask_b32_e64 v52, 1.0, v115, s[2:3]
	v_add_f32_e32 v79, v75, v73
	v_cvt_pk_bf16_f32 v112, v127, v2
	v_pk_add_f32 v[80:81], v[78:79], v[76:77]
	v_fma_f32 v77, v113, 1.0, -v159
	v_pk_add_f32 v[80:81], v[80:81], v[80:81] op_sel_hi:[0,1]
	v_fma_f32 v79, v82, 1.0, -v159
	v_exp_f32_e32 v77, v77
	v_exp_f32_e32 v79, v79
	v_fma_f32 v80, v114, 1.0, -v159
	v_fma_f32 v82, v83, 1.0, -v159
	v_exp_f32_e32 v80, v80
	v_exp_f32_e32 v82, v82
	v_add_f32_e32 v83, v79, v77
	v_cvt_pk_bf16_f32 v113, v53, v56
	v_cvt_pk_bf16_f32 v114, v57, v60
	v_pk_add_f32 v[100:101], v[82:83], v[80:81]
	v_mul_f32_e32 v83, v152, v115
	v_add_f32_e32 v81, v100, v101
	v_cndmask_b32_e64 v83, v152, v83, s[2:3]
	v_add_f32_e32 v152, v83, v81
	v_cvt_pk_bf16_f32 v115, v61, v64
	v_cvt_pk_bf16_f32 v108, v65, v68
	v_cvt_pk_bf16_f32 v109, v69, v72
	v_cvt_pk_bf16_f32 v110, v73, v76
	v_cvt_pk_bf16_f32 v111, v77, v80
	v_cvt_pk_bf16_f32 v104, v128, v54
	v_cvt_pk_bf16_f32 v105, v55, v58
	v_cvt_pk_bf16_f32 v106, v59, v62
	v_cvt_pk_bf16_f32 v107, v63, v66
	v_cvt_pk_bf16_f32 v100, v67, v70
	v_cvt_pk_bf16_f32 v101, v71, v74
	v_cvt_pk_bf16_f32 v102, v75, v78
	v_cvt_pk_bf16_f32 v103, v79, v82
	s_branch .LBB0_877

.LBB0_883:
	s_cmp_gt_i32 s34, s21
	s_cbranch_scc1 .LBB0_885
	v_lshl_or_b32 v2, s34, 6, v154
	v_or_b32_e32 v120, 32, v2
	v_cmp_le_i32_e32 vcc, v120, v153
	s_nop 1
	v_cndmask_b32_e32 v120, v230, v84, vcc
	v_cmp_le_i32_e32 vcc, v2, v153
	v_or_b32_e32 v84, 33, v2
	s_nop 0
	v_cndmask_b32_e32 v36, v230, v36, vcc
	v_cmp_lt_i32_e32 vcc, v2, v153
	s_nop 1
	v_cndmask_b32_e32 v37, v230, v37, vcc
	v_cmp_le_i32_e32 vcc, v84, v153
	v_or_b32_e32 v84, 2, v2
	s_nop 0
	v_cndmask_b32_e32 v85, v230, v85, vcc
	v_cmp_le_i32_e32 vcc, v84, v153
	s_nop 1
	v_cndmask_b32_e32 v121, v230, v38, vcc
	v_or_b32_e32 v38, 34, v2
	v_cmp_le_i32_e32 vcc, v38, v153
	v_or_b32_e32 v38, 3, v2
	s_nop 0
	v_cndmask_b32_e32 v86, v230, v86, vcc
	v_cmp_le_i32_e32 vcc, v38, v153
	v_or_b32_e32 v38, 35, v2
	s_nop 0
	v_cndmask_b32_e32 v122, v230, v39, vcc
	v_cmp_le_i32_e32 vcc, v38, v153
	v_or_b32_e32 v38, 8, v2
	v_max_f32_e32 v39, v159, v159
	v_cndmask_b32_e32 v87, v230, v87, vcc
	v_cmp_le_i32_e32 vcc, v38, v153
	v_or_b32_e32 v38, 40, v2
	s_nop 0
	v_cndmask_b32_e32 v123, v230, v40, vcc
	v_cmp_le_i32_e32 vcc, v38, v153
	v_or_b32_e32 v38, 9, v2
	s_nop 0
	v_cndmask_b32_e32 v88, v230, v88, vcc
	v_cmp_le_i32_e32 vcc, v38, v153
	v_or_b32_e32 v38, 41, v2
	s_nop 0
	v_cndmask_b32_e32 v124, v230, v41, vcc
	v_cmp_le_i32_e32 vcc, v38, v153
	v_or_b32_e32 v38, 10, v2
	s_nop 0
	v_cndmask_b32_e32 v89, v230, v89, vcc
	v_cmp_le_i32_e32 vcc, v38, v153
	v_or_b32_e32 v38, 42, v2
	s_nop 0
	v_cndmask_b32_e32 v125, v230, v42, vcc
	v_cmp_le_i32_e32 vcc, v38, v153
	v_or_b32_e32 v38, 11, v2
	s_nop 0
	v_cndmask_b32_e32 v90, v230, v90, vcc
	v_cmp_le_i32_e32 vcc, v38, v153
	v_or_b32_e32 v38, 43, v2
	s_nop 0
	v_cndmask_b32_e32 v128, v230, v43, vcc
	v_cmp_le_i32_e32 vcc, v38, v153
	v_or_b32_e32 v38, 16, v2
	s_nop 0
	v_cndmask_b32_e32 v91, v230, v91, vcc
	v_cmp_le_i32_e32 vcc, v38, v153
	v_or_b32_e32 v38, 48, v2
	s_nop 0
	v_cndmask_b32_e32 v129, v230, v44, vcc
	v_cmp_le_i32_e32 vcc, v38, v153
	v_or_b32_e32 v38, 17, v2
	s_nop 0
	v_cndmask_b32_e32 v92, v230, v92, vcc
	v_cmp_le_i32_e32 vcc, v38, v153
	v_or_b32_e32 v38, 49, v2
	s_nop 0
	v_cndmask_b32_e32 v130, v230, v45, vcc
	v_cmp_le_i32_e32 vcc, v38, v153
	v_or_b32_e32 v38, 18, v2
	s_nop 0
	v_cndmask_b32_e32 v93, v230, v93, vcc
	v_cmp_le_i32_e32 vcc, v38, v153
	v_or_b32_e32 v38, 50, v2
	s_nop 0
	v_cndmask_b32_e32 v131, v230, v46, vcc
	v_cmp_le_i32_e32 vcc, v38, v153
	v_or_b32_e32 v38, 19, v2
	s_nop 0
	v_cndmask_b32_e32 v94, v230, v94, vcc
	v_cmp_le_i32_e32 vcc, v38, v153
	v_or_b32_e32 v38, 51, v2
	s_nop 0
	v_cndmask_b32_e32 v132, v230, v47, vcc
	v_cmp_le_i32_e32 vcc, v38, v153
	v_or_b32_e32 v38, 24, v2
	s_nop 0
	v_cndmask_b32_e32 v95, v230, v95, vcc
	v_cmp_le_i32_e32 vcc, v38, v153
	v_or_b32_e32 v38, 56, v2
	s_nop 0
	v_cndmask_b32_e32 v133, v230, v48, vcc
	v_cmp_le_i32_e32 vcc, v38, v153
	v_or_b32_e32 v38, 25, v2
	s_nop 0
	v_cndmask_b32_e32 v134, v230, v96, vcc
	v_cmp_le_i32_e32 vcc, v38, v153
	v_or_b32_e32 v38, 57, v2
	s_nop 0
	v_cndmask_b32_e32 v135, v230, v49, vcc
	v_cmp_le_i32_e32 vcc, v38, v153
	v_or_b32_e32 v38, 26, v2
	s_nop 0
	v_cndmask_b32_e32 v136, v230, v97, vcc
	v_cmp_le_i32_e32 vcc, v38, v153
	v_or_b32_e32 v38, 58, v2
	s_nop 0
	v_cndmask_b32_e32 v50, v230, v50, vcc
	v_cmp_le_i32_e32 vcc, v38, v153
	v_or_b32_e32 v38, 27, v2
	v_or_b32_e32 v2, 59, v2
	v_cndmask_b32_e32 v137, v230, v98, vcc
	v_cmp_le_i32_e32 vcc, v38, v153
	s_nop 1
	v_cndmask_b32_e32 v51, v230, v51, vcc
	v_cmp_le_i32_e32 vcc, v2, v153
	v_max3_f32 v2, v36, v120, v37
	v_max3_f32 v38, v85, v121, v86
	s_nop 0
	v_max3_f32 v2, v2, v122, v87
	v_max3_f32 v38, v38, v123, v88
	s_nop 0
	v_cndmask_b32_e32 v138, v230, v99, vcc
	v_max3_f32 v2, v2, v124, v89
	v_max3_f32 v38, v38, v125, v90
	s_nop 0
	v_max3_f32 v2, v2, v128, v91
	v_max3_f32 v38, v38, v129, v92
	s_nop 0
	v_max3_f32 v2, v2, v130, v93
	v_max3_f32 v38, v38, v131, v94
	s_nop 0
	v_max3_f32 v2, v2, v132, v95
	v_max3_f32 v38, v38, v133, v134
	s_nop 0
	v_max3_f32 v2, v2, v135, v136
	v_max3_f32 v38, v38, v50, v137
	s_nop 0
	v_max3_f32 v2, v2, v38, v51
	v_max_f32_e32 v38, v138, v138
	v_max_f32_e32 v2, v2, v2
	v_max_f32_e32 v2, v2, v38
	v_mov_b32_e32 v38, v2
	s_nop 1
	v_permlane32_swap_b32_e32 v2, v38
	v_max_f32_e32 v38, v38, v38
	v_max_f32_e32 v2, v2, v2
	v_max_f32_e32 v2, v2, v38
	v_mul_f32_e32 v2, 0x3f800000, v2
	v_add_f32_e32 v38, 0x41000000, v159
	v_cmp_gt_f32_e32 vcc, v2, v38
	s_cmp_lg_u64 vcc, 0
	v_max_f32_e32 v39, v39, v2
	s_cselect_b64 s[2:3], -1, 0
	v_sub_f32_e32 v40, v159, v39
	v_cndmask_b32_e64 v159, v159, v39, s[2:3]
	v_fma_f32 v2, v36, 1.0, -v159
	v_exp_f32_e32 v140, v2
	v_fma_f32 v2, v120, 1.0, -v159
	v_exp_f32_e32 v141, v2
	v_fma_f32 v2, v37, 1.0, -v159
	v_fma_f32 v36, v85, 1.0, -v159
	v_exp_f32_e32 v2, v2
	v_exp_f32_e32 v36, v36
	v_add_f32_e32 v37, v141, v140
	v_exp_f32_e32 v139, v40
	v_fma_f32 v40, v87, 1.0, -v159
	v_pk_add_f32 v[38:39], v[36:37], v[2:3]
	v_fma_f32 v37, v121, 1.0, -v159
	v_pk_add_f32 v[38:39], v[38:39], v[38:39] op_sel_hi:[0,1]
	v_fma_f32 v38, v86, 1.0, -v159
	v_exp_f32_e32 v37, v37
	v_exp_f32_e32 v85, v38
	v_fma_f32 v38, v122, 1.0, -v159
	v_exp_f32_e32 v38, v38
	v_exp_f32_e32 v42, v40
	v_add_f32_e32 v43, v85, v37
	v_fma_f32 v44, v89, 1.0, -v159
	v_exp_f32_e32 v86, v44
	v_pk_add_f32 v[40:41], v[42:43], v[38:39]
	v_fma_f32 v39, v123, 1.0, -v159
	v_pk_add_f32 v[40:41], v[40:41], v[40:41] op_sel_hi:[0,1]
	v_fma_f32 v40, v88, 1.0, -v159
	v_exp_f32_e32 v39, v39
	v_exp_f32_e32 v43, v40
	v_fma_f32 v40, v124, 1.0, -v159
	v_exp_f32_e32 v40, v40
	v_fma_f32 v46, v91, 1.0, -v159
	v_add_f32_e32 v87, v43, v39
	v_exp_f32_e32 v88, v46
	v_pk_add_f32 v[44:45], v[86:87], v[40:41]
	v_fma_f32 v41, v125, 1.0, -v159
	v_pk_add_f32 v[44:45], v[44:45], v[44:45] op_sel_hi:[0,1]
	v_fma_f32 v44, v90, 1.0, -v159
	v_exp_f32_e32 v41, v41
	v_exp_f32_e32 v87, v44
	v_fma_f32 v44, v128, 1.0, -v159
	v_exp_f32_e32 v44, v44
	v_fma_f32 v48, v93, 1.0, -v159
	v_add_f32_e32 v89, v87, v41
	v_exp_f32_e32 v90, v48
	v_pk_add_f32 v[46:47], v[88:89], v[44:45]
	v_fma_f32 v45, v129, 1.0, -v159
	v_pk_add_f32 v[46:47], v[46:47], v[46:47] op_sel_hi:[0,1]
	v_fma_f32 v46, v92, 1.0, -v159
	v_exp_f32_e32 v45, v45
	v_exp_f32_e32 v89, v46
	v_fma_f32 v46, v130, 1.0, -v159
	v_exp_f32_e32 v46, v46
	v_cndmask_b32_e64 v84, 1.0, v139, s[2:3]
	v_add_f32_e32 v91, v89, v45
	v_pk_add_f32 v[48:49], v[90:91], v[46:47]
	s_nop 0
	v_pk_add_f32 v[92:93], v[48:49], v[48:49] op_sel_hi:[0,1]
	v_fma_f32 v48, v94, 1.0, -v159
	v_fma_f32 v47, v131, 1.0, -v159
	v_exp_f32_e32 v91, v48
	v_fma_f32 v48, v132, 1.0, -v159
	v_exp_f32_e32 v47, v47
	v_exp_f32_e32 v92, v48
	v_fma_f32 v48, v95, 1.0, -v159
	v_exp_f32_e32 v94, v48
	v_add_f32_e32 v95, v91, v47
	v_pk_add_f32 v[48:49], v[94:95], v[92:93]
	s_nop 0
	v_pk_add_f32 v[96:97], v[48:49], v[48:49] op_sel_hi:[0,1]
	v_fma_f32 v48, v133, 1.0, -v159
	v_exp_f32_e32 v93, v48
	v_fma_f32 v48, v134, 1.0, -v159
	v_exp_f32_e32 v95, v48
	v_fma_f32 v48, v135, 1.0, -v159
	v_exp_f32_e32 v96, v48
	v_fma_f32 v48, v136, 1.0, -v159
	v_exp_f32_e32 v98, v48
	v_add_f32_e32 v99, v95, v93
	v_pk_add_f32 v[48:49], v[98:99], v[96:97]
	s_nop 0
	v_pk_add_f32 v[120:121], v[48:49], v[48:49] op_sel_hi:[0,1]
	v_fma_f32 v48, v50, 1.0, -v159
	v_exp_f32_e32 v97, v48
	v_fma_f32 v48, v137, 1.0, -v159
	v_exp_f32_e32 v99, v48
	v_fma_f32 v48, v51, 1.0, -v159
	v_exp_f32_e32 v120, v48
	v_fma_f32 v48, v138, 1.0, -v159
	v_exp_f32_e32 v122, v48
	v_add_f32_e32 v123, v99, v97
	v_cvt_pk_bf16_f32 v50, v39, v40
	v_cvt_pk_bf16_f32 v51, v41, v44
	v_pk_add_f32 v[48:49], v[122:123], v[120:121]
	v_cvt_pk_bf16_f32 v44, v45, v46
	v_add_f32_e32 v48, v48, v49
	v_mul_f32_e32 v49, v152, v139
	v_cndmask_b32_e64 v49, v152, v49, s[2:3]
	v_add_f32_e32 v152, v49, v48
	v_cvt_pk_bf16_f32 v48, v140, v2
	v_cvt_pk_bf16_f32 v49, v37, v38
	v_cvt_pk_bf16_f32 v45, v47, v92
	v_cvt_pk_bf16_f32 v46, v93, v96
	v_cvt_pk_bf16_f32 v47, v97, v120
	v_cvt_pk_bf16_f32 v40, v141, v36
	v_cvt_pk_bf16_f32 v41, v85, v42
	v_cvt_pk_bf16_f32 v42, v43, v86
	v_cvt_pk_bf16_f32 v43, v87, v88
	v_cvt_pk_bf16_f32 v36, v89, v90
	v_cvt_pk_bf16_f32 v37, v91, v94
	v_cvt_pk_bf16_f32 v38, v95, v98
	v_cvt_pk_bf16_f32 v39, v99, v122
	s_branch .LBB0_886

.LBB0_890:
	s_add_i32 s35, s35, s22
	s_waitcnt vmcnt(0)
	ds_write_b128 v151, v[116:119] offset:26624
	s_waitcnt lgkmcnt(0)
	s_barrier
	buffer_load_dwordx4 v[84:87], v150, s[12:15], s35 offen
	s_sub_i32 s5, s5, s23
	s_cmp_gt_i32 s5, s21
	s_cbranch_scc1 .LBB0_892
	v_lshl_or_b32 v2, s5, 6, v154
	v_or_b32_e32 v88, 32, v2
	v_cmp_le_i32_e32 vcc, v88, v153
	s_nop 1
	v_cndmask_b32_e32 v88, v230, v68, vcc
	v_cmp_le_i32_e32 vcc, v2, v153
	v_or_b32_e32 v68, 33, v2
	s_nop 0
	v_cndmask_b32_e32 v52, v230, v52, vcc
	v_cmp_lt_i32_e32 vcc, v2, v153
	s_nop 1
	v_cndmask_b32_e32 v53, v230, v53, vcc
	v_cmp_le_i32_e32 vcc, v68, v153
	v_or_b32_e32 v68, 2, v2
	s_nop 0
	v_cndmask_b32_e32 v69, v230, v69, vcc
	v_cmp_le_i32_e32 vcc, v68, v153
	s_nop 1
	v_cndmask_b32_e32 v89, v230, v54, vcc
	v_or_b32_e32 v54, 34, v2
	v_cmp_le_i32_e32 vcc, v54, v153
	v_or_b32_e32 v54, 3, v2
	s_nop 0
	v_cndmask_b32_e32 v70, v230, v70, vcc
	v_cmp_le_i32_e32 vcc, v54, v153
	v_or_b32_e32 v54, 35, v2
	s_nop 0
	v_cndmask_b32_e32 v90, v230, v55, vcc
	v_cmp_le_i32_e32 vcc, v54, v153
	v_or_b32_e32 v54, 8, v2
	v_max_f32_e32 v55, v159, v159
	v_cndmask_b32_e32 v71, v230, v71, vcc
	v_cmp_le_i32_e32 vcc, v54, v153
	v_or_b32_e32 v54, 40, v2
	s_nop 0
	v_cndmask_b32_e32 v91, v230, v56, vcc
	v_cmp_le_i32_e32 vcc, v54, v153
	v_or_b32_e32 v54, 9, v2
	s_nop 0
	v_cndmask_b32_e32 v72, v230, v72, vcc
	v_cmp_le_i32_e32 vcc, v54, v153
	v_or_b32_e32 v54, 41, v2
	s_nop 0
	v_cndmask_b32_e32 v92, v230, v57, vcc
	v_cmp_le_i32_e32 vcc, v54, v153
	v_or_b32_e32 v54, 10, v2
	s_nop 0
	v_cndmask_b32_e32 v73, v230, v73, vcc
	v_cmp_le_i32_e32 vcc, v54, v153
	v_or_b32_e32 v54, 42, v2
	s_nop 0
	v_cndmask_b32_e32 v93, v230, v58, vcc
	v_cmp_le_i32_e32 vcc, v54, v153
	v_or_b32_e32 v54, 11, v2
	s_nop 0
	v_cndmask_b32_e32 v74, v230, v74, vcc
	v_cmp_le_i32_e32 vcc, v54, v153
	v_or_b32_e32 v54, 43, v2
	s_nop 0
	v_cndmask_b32_e32 v94, v230, v59, vcc
	v_cmp_le_i32_e32 vcc, v54, v153
	v_or_b32_e32 v54, 16, v2
	s_nop 0
	v_cndmask_b32_e32 v75, v230, v75, vcc
	v_cmp_le_i32_e32 vcc, v54, v153
	v_or_b32_e32 v54, 48, v2
	s_nop 0
	v_cndmask_b32_e32 v95, v230, v60, vcc
	v_cmp_le_i32_e32 vcc, v54, v153
	v_or_b32_e32 v54, 17, v2
	s_nop 0
	v_cndmask_b32_e32 v76, v230, v76, vcc
	v_cmp_le_i32_e32 vcc, v54, v153
	v_or_b32_e32 v54, 49, v2
	s_nop 0
	v_cndmask_b32_e32 v96, v230, v61, vcc
	v_cmp_le_i32_e32 vcc, v54, v153
	v_or_b32_e32 v54, 18, v2
	s_nop 0
	v_cndmask_b32_e32 v77, v230, v77, vcc
	v_cmp_le_i32_e32 vcc, v54, v153
	v_or_b32_e32 v54, 50, v2
	s_nop 0
	v_cndmask_b32_e32 v97, v230, v62, vcc
	v_cmp_le_i32_e32 vcc, v54, v153
	v_or_b32_e32 v54, 19, v2
	s_nop 0
	v_cndmask_b32_e32 v78, v230, v78, vcc
	v_cmp_le_i32_e32 vcc, v54, v153
	v_or_b32_e32 v54, 51, v2
	s_nop 0
	v_cndmask_b32_e32 v98, v230, v63, vcc
	v_cmp_le_i32_e32 vcc, v54, v153
	v_or_b32_e32 v54, 24, v2
	s_nop 0
	v_cndmask_b32_e32 v79, v230, v79, vcc
	v_cmp_le_i32_e32 vcc, v54, v153
	v_or_b32_e32 v54, 56, v2
	s_nop 0
	v_cndmask_b32_e32 v99, v230, v64, vcc
	v_cmp_le_i32_e32 vcc, v54, v153
	v_or_b32_e32 v54, 25, v2
	s_nop 0
	v_cndmask_b32_e32 v100, v230, v80, vcc
	v_cmp_le_i32_e32 vcc, v54, v153
	v_or_b32_e32 v54, 57, v2
	s_nop 0
	v_cndmask_b32_e32 v101, v230, v65, vcc
	v_cmp_le_i32_e32 vcc, v54, v153
	v_or_b32_e32 v54, 26, v2
	s_nop 0
	v_cndmask_b32_e32 v102, v230, v81, vcc
	v_cmp_le_i32_e32 vcc, v54, v153
	v_or_b32_e32 v54, 58, v2
	s_nop 0
	v_cndmask_b32_e32 v66, v230, v66, vcc
	v_cmp_le_i32_e32 vcc, v54, v153
	v_or_b32_e32 v54, 27, v2
	v_or_b32_e32 v2, 59, v2
	v_cndmask_b32_e32 v103, v230, v82, vcc
	v_cmp_le_i32_e32 vcc, v54, v153
	s_nop 1
	v_cndmask_b32_e32 v67, v230, v67, vcc
	v_cmp_le_i32_e32 vcc, v2, v153
	v_max3_f32 v2, v52, v88, v53
	v_max3_f32 v54, v69, v89, v70
	s_nop 0
	v_max3_f32 v2, v2, v90, v71
	v_max3_f32 v54, v54, v91, v72
	s_nop 0
	v_cndmask_b32_e32 v104, v230, v83, vcc
	v_max3_f32 v2, v2, v92, v73
	v_max3_f32 v54, v54, v93, v74
	s_nop 0
	v_max3_f32 v2, v2, v94, v75
	v_max3_f32 v54, v54, v95, v76
	s_nop 0
	v_max3_f32 v2, v2, v96, v77
	v_max3_f32 v54, v54, v97, v78
	s_nop 0
	v_max3_f32 v2, v2, v98, v79
	v_max3_f32 v54, v54, v99, v100
	s_nop 0
	v_max3_f32 v2, v2, v101, v102
	v_max3_f32 v54, v54, v66, v103
	s_nop 0
	v_max3_f32 v2, v2, v54, v67
	v_max_f32_e32 v54, v104, v104
	v_max_f32_e32 v2, v2, v2
	v_max_f32_e32 v2, v2, v54
	v_mov_b32_e32 v54, v2
	s_nop 1
	v_permlane32_swap_b32_e32 v2, v54
	v_max_f32_e32 v54, v54, v54
	v_max_f32_e32 v2, v2, v2
	v_max_f32_e32 v2, v2, v54
	v_mul_f32_e32 v2, 0x3f800000, v2
	v_add_f32_e32 v54, 0x41000000, v159
	v_cmp_gt_f32_e32 vcc, v2, v54
	s_cmp_lg_u64 vcc, 0
	v_max_f32_e32 v55, v55, v2
	s_cselect_b64 s[2:3], -1, 0
	v_cndmask_b32_e64 v106, v159, v55, s[2:3]
	v_fma_f32 v2, v52, 1.0, -v106
	v_exp_f32_e32 v107, v2
	v_fma_f32 v2, v88, 1.0, -v106
	v_exp_f32_e32 v108, v2
	v_fma_f32 v2, v53, 1.0, -v106
	v_fma_f32 v52, v69, 1.0, -v106
	v_exp_f32_e32 v2, v2
	v_exp_f32_e32 v52, v52
	v_add_f32_e32 v53, v108, v107
	v_sub_f32_e32 v56, v159, v55
	v_exp_f32_e32 v105, v56
	v_pk_add_f32 v[54:55], v[52:53], v[2:3]
	v_fma_f32 v53, v89, 1.0, -v106
	v_pk_add_f32 v[54:55], v[54:55], v[54:55] op_sel_hi:[0,1]
	v_fma_f32 v54, v70, 1.0, -v106
	v_exp_f32_e32 v53, v53
	v_exp_f32_e32 v69, v54
	v_fma_f32 v54, v90, 1.0, -v106
	v_fma_f32 v56, v71, 1.0, -v106
	v_exp_f32_e32 v54, v54
	v_exp_f32_e32 v58, v56
	v_add_f32_e32 v59, v69, v53
	v_fma_f32 v60, v73, 1.0, -v106
	v_exp_f32_e32 v70, v60
	v_pk_add_f32 v[56:57], v[58:59], v[54:55]
	v_fma_f32 v55, v91, 1.0, -v106
	v_pk_add_f32 v[56:57], v[56:57], v[56:57] op_sel_hi:[0,1]
	v_fma_f32 v56, v72, 1.0, -v106
	v_exp_f32_e32 v55, v55
	v_exp_f32_e32 v59, v56
	v_fma_f32 v56, v92, 1.0, -v106
	v_exp_f32_e32 v56, v56
	v_fma_f32 v62, v75, 1.0, -v106
	v_add_f32_e32 v71, v59, v55
	v_exp_f32_e32 v72, v62
	v_pk_add_f32 v[60:61], v[70:71], v[56:57]
	v_fma_f32 v57, v93, 1.0, -v106
	v_pk_add_f32 v[60:61], v[60:61], v[60:61] op_sel_hi:[0,1]
	v_fma_f32 v60, v74, 1.0, -v106
	v_exp_f32_e32 v57, v57
	v_exp_f32_e32 v71, v60
	v_fma_f32 v60, v94, 1.0, -v106
	v_exp_f32_e32 v60, v60
	v_fma_f32 v64, v77, 1.0, -v106
	v_add_f32_e32 v73, v71, v57
	v_exp_f32_e32 v74, v64
	v_pk_add_f32 v[62:63], v[72:73], v[60:61]
	v_fma_f32 v61, v95, 1.0, -v106
	v_pk_add_f32 v[62:63], v[62:63], v[62:63] op_sel_hi:[0,1]
	v_fma_f32 v62, v76, 1.0, -v106
	v_exp_f32_e32 v61, v61
	v_exp_f32_e32 v73, v62
	v_fma_f32 v62, v96, 1.0, -v106
	v_exp_f32_e32 v62, v62
	v_cndmask_b32_e64 v68, 1.0, v105, s[2:3]
	v_add_f32_e32 v75, v73, v61
	v_pk_add_f32 v[64:65], v[74:75], v[62:63]
	s_nop 0
	v_pk_add_f32 v[76:77], v[64:65], v[64:65] op_sel_hi:[0,1]
	v_fma_f32 v64, v78, 1.0, -v106
	v_fma_f32 v63, v97, 1.0, -v106
	v_exp_f32_e32 v75, v64
	v_fma_f32 v64, v98, 1.0, -v106
	v_exp_f32_e32 v63, v63
	v_exp_f32_e32 v76, v64
	v_fma_f32 v64, v79, 1.0, -v106
	v_exp_f32_e32 v78, v64
	v_add_f32_e32 v79, v75, v63
	v_pk_add_f32 v[64:65], v[78:79], v[76:77]
	s_nop 0
	v_pk_add_f32 v[80:81], v[64:65], v[64:65] op_sel_hi:[0,1]
	v_fma_f32 v64, v99, 1.0, -v106
	v_exp_f32_e32 v77, v64
	v_fma_f32 v64, v100, 1.0, -v106
	v_exp_f32_e32 v79, v64
	v_fma_f32 v64, v101, 1.0, -v106
	v_exp_f32_e32 v80, v64
	v_fma_f32 v64, v102, 1.0, -v106
	v_exp_f32_e32 v82, v64
	v_add_f32_e32 v83, v79, v77
	v_pk_add_f32 v[64:65], v[82:83], v[80:81]
	s_nop 0
	v_pk_add_f32 v[88:89], v[64:65], v[64:65] op_sel_hi:[0,1]
	v_fma_f32 v64, v66, 1.0, -v106
	v_exp_f32_e32 v81, v64
	v_fma_f32 v64, v103, 1.0, -v106
	v_exp_f32_e32 v83, v64
	v_fma_f32 v64, v67, 1.0, -v106
	v_exp_f32_e32 v88, v64
	v_fma_f32 v64, v104, 1.0, -v106
	v_exp_f32_e32 v90, v64
	v_add_f32_e32 v91, v83, v81
	v_cvt_pk_bf16_f32 v66, v55, v56
	v_cvt_pk_bf16_f32 v67, v57, v60
	v_pk_add_f32 v[64:65], v[90:91], v[88:89]
	v_cvt_pk_bf16_f32 v60, v61, v62
	v_add_f32_e32 v64, v64, v65
	v_mul_f32_e32 v65, v152, v105
	v_cndmask_b32_e64 v65, v152, v65, s[2:3]
	v_add_f32_e32 v152, v65, v64
	v_cvt_pk_bf16_f32 v64, v107, v2
	v_cvt_pk_bf16_f32 v65, v53, v54
	v_cvt_pk_bf16_f32 v61, v63, v76
	v_cvt_pk_bf16_f32 v62, v77, v80
	v_cvt_pk_bf16_f32 v63, v81, v88
	v_cvt_pk_bf16_f32 v56, v108, v52
	v_cvt_pk_bf16_f32 v57, v69, v58
	v_cvt_pk_bf16_f32 v58, v59, v70
	v_cvt_pk_bf16_f32 v59, v71, v72
	v_cvt_pk_bf16_f32 v52, v73, v74
	v_cvt_pk_bf16_f32 v53, v75, v78
	v_cvt_pk_bf16_f32 v54, v79, v82
	v_cvt_pk_bf16_f32 v55, v83, v90
	s_branch .LBB0_893
